# v9 + k-tile bodies of the 256x128 stream GEMMs re-scheduled: out-proj and in-proj tail read the 2nd k-half fragments into spare registers under the 1st half MFMAs, branch-proj and latent-DFT hoist the
# speedup vs baseline: 1.0615x; 1.0062x over previous
.LBB0_446:
	v_add_u32_e32 v0, v82, v90
	v_add_u32_e32 v99, v88, v89
	ds_read_b128 v[100:103], v0 offset:32768
	ds_read_b128 v[108:111], v0 offset:34816
	ds_read_b128 v[104:107], v92
	ds_read_b128 v[112:115], v93
	ds_read_b128 v[116:119], v94
	ds_read_b128 v[120:123], v99
	ds_read_b128 v[124:127], v0 offset:36864
	ds_read_b128 v[128:131], v0 offset:38912
	s_add_i32 s6, s6, 1
	s_cmp_lg_u32 s6, 32
	s_waitcnt lgkmcnt(5)
	v_mfma_f32_16x16x32_bf16 v[62:65], v[100:103], v[104:107], v[62:65]
	v_mfma_f32_16x16x32_bf16 v[58:61], v[108:111], v[104:107], v[58:61]
	s_waitcnt lgkmcnt(4)
	v_mfma_f32_16x16x32_bf16 v[46:49], v[100:103], v[112:115], v[46:49]
	v_mfma_f32_16x16x32_bf16 v[42:45], v[108:111], v[112:115], v[42:45]
	ds_read_b128 v[132:135], v0 offset:33792
	ds_read_b128 v[136:139], v0 offset:35840
	ds_read_b128 v[140:143], v0 offset:39936
	ds_read_b128 v[144:147], v0 offset:37888
	ds_read_b128 v[152:155], v92 offset:1024
	ds_read_b128 v[156:159], v93 offset:1024
	ds_read_b128 v[160:163], v94 offset:1024
	ds_read_b128 v[164:167], v99 offset:1024
	s_waitcnt lgkmcnt(9)
	v_mfma_f32_16x16x32_bf16 v[54:57], v[124:127], v[104:107], v[54:57]
	v_mfma_f32_16x16x32_bf16 v[38:41], v[124:127], v[112:115], v[38:41]
	v_mfma_f32_16x16x32_bf16 v[30:33], v[100:103], v[116:119], v[30:33]
	v_mfma_f32_16x16x32_bf16 v[26:29], v[108:111], v[116:119], v[26:29]
	s_waitcnt lgkmcnt(8)
	v_mfma_f32_16x16x32_bf16 v[50:53], v[128:131], v[104:107], v[50:53]
	v_mfma_f32_16x16x32_bf16 v[34:37], v[128:131], v[112:115], v[34:37]
	v_mfma_f32_16x16x32_bf16 v[22:25], v[124:127], v[116:119], v[22:25]
	v_mfma_f32_16x16x32_bf16 v[18:21], v[128:131], v[116:119], v[18:21]
	v_mfma_f32_16x16x32_bf16 v[14:17], v[100:103], v[120:123], v[14:17]
	v_mfma_f32_16x16x32_bf16 v[10:13], v[108:111], v[120:123], v[10:13]
	v_mfma_f32_16x16x32_bf16 v[6:9], v[124:127], v[120:123], v[6:9]
	v_mfma_f32_16x16x32_bf16 v[2:5], v[128:131], v[120:123], v[2:5]
	s_waitcnt lgkmcnt(3)
	v_mfma_f32_16x16x32_bf16 v[62:65], v[132:135], v[152:155], v[62:65]
	v_mfma_f32_16x16x32_bf16 v[58:61], v[136:139], v[152:155], v[58:61]
	v_mfma_f32_16x16x32_bf16 v[54:57], v[144:147], v[152:155], v[54:57]
	v_mfma_f32_16x16x32_bf16 v[50:53], v[140:143], v[152:155], v[50:53]
	s_waitcnt lgkmcnt(2)
	v_mfma_f32_16x16x32_bf16 v[46:49], v[132:135], v[156:159], v[46:49]
	v_mfma_f32_16x16x32_bf16 v[42:45], v[136:139], v[156:159], v[42:45]
	v_mfma_f32_16x16x32_bf16 v[38:41], v[144:147], v[156:159], v[38:41]
	v_mfma_f32_16x16x32_bf16 v[34:37], v[140:143], v[156:159], v[34:37]
	s_waitcnt lgkmcnt(1)
	v_mfma_f32_16x16x32_bf16 v[30:33], v[132:135], v[160:163], v[30:33]
	v_mfma_f32_16x16x32_bf16 v[26:29], v[136:139], v[160:163], v[26:29]
	v_mfma_f32_16x16x32_bf16 v[22:25], v[144:147], v[160:163], v[22:25]
	v_mfma_f32_16x16x32_bf16 v[18:21], v[140:143], v[160:163], v[18:21]
	s_waitcnt lgkmcnt(0)
	v_mfma_f32_16x16x32_bf16 v[14:17], v[132:135], v[164:167], v[14:17]
	v_mfma_f32_16x16x32_bf16 v[10:13], v[136:139], v[164:167], v[10:13]
	v_mfma_f32_16x16x32_bf16 v[6:9], v[144:147], v[164:167], v[6:9]
	v_mfma_f32_16x16x32_bf16 v[2:5], v[140:143], v[164:167], v[2:5]
	s_cbranch_scc1 .LBB0_512
	v_cndmask_b32_e64 v99, 0, 1, s[50:51]
	v_mov_b32_e32 v0, v196
	v_cmp_ne_u32_e64 s[40:41], 1, v99
	s_andn2_b64 vcc, exec, s[50:51]
	s_mov_b64 s[6:7], -1
	s_cbranch_vccnz .LBB0_449
	s_mov_b64 s[6:7], 0

.LBB0_515:
	v_add_u32_e32 v0, v91, v87
	ds_read_b128 v[100:103], v98
	ds_read_b128 v[108:111], v98 offset:2048
	ds_read_b128 v[104:107], v95
	ds_read_b128 v[120:123], v0
	ds_read_b128 v[112:115], v96
	ds_read_b128 v[116:119], v97
	ds_read_b128 v[124:127], v98 offset:4096
	ds_read_b128 v[128:131], v98 offset:6144
	s_add_i32 s6, s6, 1
	s_cmp_lg_u32 s6, 32
	s_waitcnt lgkmcnt(5)
	v_mfma_f32_16x16x32_bf16 v[62:65], v[100:103], v[104:107], v[62:65]
	v_mfma_f32_16x16x32_bf16 v[58:61], v[108:111], v[104:107], v[58:61]
	s_waitcnt lgkmcnt(4)
	v_mfma_f32_16x16x32_bf16 v[46:49], v[100:103], v[120:123], v[46:49]
	v_mfma_f32_16x16x32_bf16 v[42:45], v[108:111], v[120:123], v[42:45]
	ds_read_b128 v[132:135], v98 offset:1024
	ds_read_b128 v[136:139], v98 offset:3072
	ds_read_b128 v[140:143], v98 offset:7168
	ds_read_b128 v[144:147], v98 offset:5120
	ds_read_b128 v[152:155], v96 offset:1024
	ds_read_b128 v[156:159], v97 offset:1024
	ds_read_b128 v[160:163], v0 offset:1024
	ds_read_b128 v[164:167], v95 offset:1024
	s_waitcnt lgkmcnt(9)
	v_mfma_f32_16x16x32_bf16 v[54:57], v[124:127], v[104:107], v[54:57]
	v_mfma_f32_16x16x32_bf16 v[38:41], v[124:127], v[120:123], v[38:41]
	v_mfma_f32_16x16x32_bf16 v[30:33], v[100:103], v[112:115], v[30:33]
	v_mfma_f32_16x16x32_bf16 v[26:29], v[108:111], v[112:115], v[26:29]
	s_waitcnt lgkmcnt(8)
	v_mfma_f32_16x16x32_bf16 v[50:53], v[128:131], v[104:107], v[50:53]
	v_mfma_f32_16x16x32_bf16 v[34:37], v[128:131], v[120:123], v[34:37]
	v_mfma_f32_16x16x32_bf16 v[22:25], v[124:127], v[112:115], v[22:25]
	v_mfma_f32_16x16x32_bf16 v[18:21], v[128:131], v[112:115], v[18:21]
	v_mfma_f32_16x16x32_bf16 v[14:17], v[100:103], v[116:119], v[14:17]
	v_mfma_f32_16x16x32_bf16 v[10:13], v[108:111], v[116:119], v[10:13]
	v_mfma_f32_16x16x32_bf16 v[6:9], v[124:127], v[116:119], v[6:9]
	v_mfma_f32_16x16x32_bf16 v[2:5], v[128:131], v[116:119], v[2:5]
	s_waitcnt lgkmcnt(3)
	v_mfma_f32_16x16x32_bf16 v[30:33], v[132:135], v[152:155], v[30:33]
	v_mfma_f32_16x16x32_bf16 v[26:29], v[136:139], v[152:155], v[26:29]
	v_mfma_f32_16x16x32_bf16 v[22:25], v[144:147], v[152:155], v[22:25]
	v_mfma_f32_16x16x32_bf16 v[18:21], v[140:143], v[152:155], v[18:21]
	s_waitcnt lgkmcnt(1)
	v_mfma_f32_16x16x32_bf16 v[46:49], v[132:135], v[160:163], v[46:49]
	v_mfma_f32_16x16x32_bf16 v[42:45], v[136:139], v[160:163], v[42:45]
	v_mfma_f32_16x16x32_bf16 v[38:41], v[144:147], v[160:163], v[38:41]
	v_mfma_f32_16x16x32_bf16 v[34:37], v[140:143], v[160:163], v[34:37]
	s_waitcnt lgkmcnt(0)
	v_mfma_f32_16x16x32_bf16 v[62:65], v[132:135], v[164:167], v[62:65]
	v_mfma_f32_16x16x32_bf16 v[58:61], v[136:139], v[164:167], v[58:61]
	v_mfma_f32_16x16x32_bf16 v[54:57], v[144:147], v[164:167], v[54:57]
	v_mfma_f32_16x16x32_bf16 v[50:53], v[140:143], v[164:167], v[50:53]
	v_mfma_f32_16x16x32_bf16 v[14:17], v[132:135], v[156:159], v[14:17]
	v_mfma_f32_16x16x32_bf16 v[10:13], v[136:139], v[156:159], v[10:13]
	v_mfma_f32_16x16x32_bf16 v[6:9], v[144:147], v[156:159], v[6:9]
	v_mfma_f32_16x16x32_bf16 v[2:5], v[140:143], v[156:159], v[2:5]
	s_cbranch_scc1 .LBB0_443
	v_cndmask_b32_e64 v99, 0, 1, s[50:51]
	v_mov_b32_e32 v0, v196
	v_cmp_ne_u32_e64 s[40:41], 1, v99
	s_andn2_b64 vcc, exec, s[50:51]
	s_mov_b64 s[2:3], -1
	s_cbranch_vccnz .LBB0_518
	s_mov_b64 s[2:3], 0

.LBB0_847:
	v_add_u32_e32 v0, v228, v238
	v_add_u32_e32 v172, v236, v237
	ds_read_b128 v[138:141], v0 offset:32768
	ds_read_b128 v[146:149], v0 offset:34816
	ds_read_b128 v[142:145], v240
	ds_read_b128 v[152:155], v241
	ds_read_b128 v[156:159], v242
	ds_read_b128 v[160:163], v172
	ds_read_b128 v[164:167], v0 offset:36864
	ds_read_b128 v[168:171], v0 offset:38912
	s_add_i32 s6, s6, 1
	s_cmp_lg_u32 s6, 64
	s_waitcnt lgkmcnt(5)
	v_mfma_f32_16x16x32_bf16 v[126:129], v[138:141], v[142:145], v[126:129]
	v_mfma_f32_16x16x32_bf16 v[122:125], v[146:149], v[142:145], v[122:125]
	s_waitcnt lgkmcnt(4)
	v_mfma_f32_16x16x32_bf16 v[110:113], v[138:141], v[152:155], v[110:113]
	v_mfma_f32_16x16x32_bf16 v[106:109], v[146:149], v[152:155], v[106:109]
	s_waitcnt lgkmcnt(1)
	v_mfma_f32_16x16x32_bf16 v[118:121], v[164:167], v[142:145], v[118:121]
	v_mfma_f32_16x16x32_bf16 v[102:105], v[164:167], v[152:155], v[102:105]
	v_mfma_f32_16x16x32_bf16 v[94:97], v[138:141], v[156:159], v[94:97]
	v_mfma_f32_16x16x32_bf16 v[90:93], v[146:149], v[156:159], v[90:93]
	s_waitcnt lgkmcnt(0)
	v_mfma_f32_16x16x32_bf16 v[114:117], v[168:171], v[142:145], v[114:117]
	v_mfma_f32_16x16x32_bf16 v[98:101], v[168:171], v[152:155], v[98:101]
	v_mfma_f32_16x16x32_bf16 v[86:89], v[164:167], v[156:159], v[86:89]
	v_mfma_f32_16x16x32_bf16 v[82:85], v[168:171], v[156:159], v[82:85]
	v_mfma_f32_16x16x32_bf16 v[78:81], v[138:141], v[160:163], v[78:81]
	v_mfma_f32_16x16x32_bf16 v[74:77], v[146:149], v[160:163], v[74:77]
	v_mfma_f32_16x16x32_bf16 v[70:73], v[164:167], v[160:163], v[70:73]
	v_mfma_f32_16x16x32_bf16 v[66:69], v[168:171], v[160:163], v[66:69]
	ds_read_b128 v[138:141], v0 offset:33792
	ds_read_b128 v[142:145], v0 offset:35840
	ds_read_b128 v[152:155], v0 offset:39936
	ds_read_b128 v[156:159], v0 offset:37888
	ds_read_b128 v[146:149], v240 offset:1024
	ds_read_b128 v[160:163], v241 offset:1024
	s_waitcnt lgkmcnt(1)
	v_mfma_f32_16x16x32_bf16 v[126:129], v[138:141], v[146:149], v[126:129]
	v_mfma_f32_16x16x32_bf16 v[122:125], v[142:145], v[146:149], v[122:125]
	v_mfma_f32_16x16x32_bf16 v[118:121], v[156:159], v[146:149], v[118:121]
	v_mfma_f32_16x16x32_bf16 v[114:117], v[152:155], v[146:149], v[114:117]
	ds_read_b128 v[146:149], v242 offset:1024
	s_waitcnt lgkmcnt(1)
	v_mfma_f32_16x16x32_bf16 v[110:113], v[138:141], v[160:163], v[110:113]
	v_mfma_f32_16x16x32_bf16 v[106:109], v[142:145], v[160:163], v[106:109]
	v_mfma_f32_16x16x32_bf16 v[102:105], v[156:159], v[160:163], v[102:105]
	v_mfma_f32_16x16x32_bf16 v[98:101], v[152:155], v[160:163], v[98:101]
	ds_read_b128 v[160:163], v172 offset:1024
	s_waitcnt lgkmcnt(1)
	v_mfma_f32_16x16x32_bf16 v[94:97], v[138:141], v[146:149], v[94:97]
	v_mfma_f32_16x16x32_bf16 v[90:93], v[142:145], v[146:149], v[90:93]
	v_mfma_f32_16x16x32_bf16 v[86:89], v[156:159], v[146:149], v[86:89]
	v_mfma_f32_16x16x32_bf16 v[82:85], v[152:155], v[146:149], v[82:85]
	s_waitcnt lgkmcnt(0)
	v_mfma_f32_16x16x32_bf16 v[78:81], v[138:141], v[160:163], v[78:81]
	v_mfma_f32_16x16x32_bf16 v[74:77], v[142:145], v[160:163], v[74:77]
	v_mfma_f32_16x16x32_bf16 v[70:73], v[156:159], v[160:163], v[70:73]
	v_mfma_f32_16x16x32_bf16 v[66:69], v[152:155], v[160:163], v[66:69]
	s_cbranch_scc1 .LBB0_860
	s_cmp_eq_u32 s22, 0
	s_cbranch_scc1 .LBB0_858
	v_mov_b32_e32 v0, v196
	v_mov_b64_e32 v[152:153], s[30:31]
	v_and_b32_e32 v247, 15, v0
	v_ashrrev_i32_e32 v248, 7, v0
	v_lshl_or_b32 v148, v248, 6, v247
	v_ashrrev_i32_e32 v149, 31, v148
	v_and_b32_e32 v138, 64, v0
	v_lshrrev_b32_e32 v0, 2, v0
	v_lshl_add_u64 v[170:171], s[42:43], 0, v[148:149]
	v_and_or_b32 v0, v0, 12, v138
	v_mad_u64_u32 v[138:139], s[6:7], v170, s90, v[152:153]
	v_mov_b32_e32 v140, v139
	v_mad_u64_u32 v[140:141], s[6:7], v171, s90, v[140:141]
	v_mov_b32_e32 v139, v140
	s_lshl_b64 s[6:7], s[46:47], 1
	v_lshl_add_u64 v[138:139], v[138:139], 0, s[6:7]
	v_lshlrev_b32_e32 v154, 1, v0
	v_mov_b32_e32 v155, v1
	v_lshl_add_u64 v[138:139], v[138:139], 0, v[154:155]
	v_or_b32_e32 v146, 16, v148
	v_lshl_add_u64 v[140:141], v[138:139], 0, s[94:95]
	v_add_co_u32_e32 v138, vcc, s10, v138
	v_ashrrev_i32_e32 v147, 31, v146
	s_nop 0
	v_addc_co_u32_e32 v139, vcc, 0, v139, vcc
	v_lshl_add_u64 v[188:189], s[42:43], 0, v[146:147]
	global_load_dwordx2 v[166:167], v[138:139], off offset:1024
	global_load_dwordx2 v[142:143], v[140:141], off offset:32
	global_load_dwordx2 v[194:195], v[140:141], off offset:64
	global_load_dwordx2 v[192:193], v[140:141], off offset:96
	v_mad_u64_u32 v[138:139], s[14:15], v188, s90, v[152:153]
	v_mov_b32_e32 v140, v139
	v_mad_u64_u32 v[140:141], s[14:15], v189, s90, v[140:141]
	v_mov_b32_e32 v139, v140
	v_lshl_add_u64 v[138:139], v[138:139], 0, s[6:7]
	v_lshl_add_u64 v[138:139], v[138:139], 0, v[154:155]
	v_or_b32_e32 v144, 32, v148
	v_lshl_add_u64 v[140:141], v[138:139], 0, s[94:95]
	v_add_co_u32_e32 v138, vcc, s10, v138
	v_ashrrev_i32_e32 v145, 31, v144
	s_nop 0
	v_addc_co_u32_e32 v139, vcc, 0, v139, vcc
	v_lshl_add_u64 v[178:179], s[42:43], 0, v[144:145]
	global_load_dwordx2 v[190:191], v[138:139], off offset:1024
	global_load_dwordx2 v[186:187], v[140:141], off offset:32
	global_load_dwordx2 v[184:185], v[140:141], off offset:64
	global_load_dwordx2 v[182:183], v[140:141], off offset:96
	v_mad_u64_u32 v[138:139], s[14:15], v178, s90, v[152:153]
	v_mov_b32_e32 v140, v139
	v_mad_u64_u32 v[140:141], s[14:15], v179, s90, v[140:141]
	v_mov_b32_e32 v139, v140
	v_lshl_add_u64 v[138:139], v[138:139], 0, s[6:7]
	v_lshl_add_u64 v[138:139], v[138:139], 0, v[154:155]
	v_lshl_add_u64 v[140:141], v[138:139], 0, s[94:95]
	v_add_co_u32_e32 v138, vcc, s10, v138
	s_nop 1
	v_addc_co_u32_e32 v139, vcc, 0, v139, vcc
	global_load_dwordx2 v[180:181], v[138:139], off offset:1024
	global_load_dwordx2 v[176:177], v[140:141], off offset:32
	global_load_dwordx2 v[174:175], v[140:141], off offset:64
	global_load_dwordx2 v[168:169], v[140:141], off offset:96
	v_or_b32_e32 v140, 48, v148
	v_ashrrev_i32_e32 v141, 31, v140
	v_lshl_add_u64 v[162:163], s[42:43], 0, v[140:141]
	v_mad_u64_u32 v[138:139], s[14:15], v162, s90, v[152:153]
	v_mov_b32_e32 v156, v139
	v_mad_u64_u32 v[156:157], s[14:15], v163, s90, v[156:157]
	v_mov_b32_e32 v139, v156
	v_lshl_add_u64 v[138:139], v[138:139], 0, s[6:7]
	v_lshl_add_u64 v[138:139], v[138:139], 0, v[154:155]
	v_lshl_add_u64 v[156:157], v[138:139], 0, s[94:95]
	v_add_co_u32_e32 v138, vcc, s10, v138
	s_nop 1
	v_addc_co_u32_e32 v139, vcc, 0, v139, vcc
	global_load_dwordx2 v[164:165], v[138:139], off offset:1024
	global_load_dwordx2 v[160:161], v[156:157], off offset:32
	global_load_dwordx2 v[158:159], v[156:157], off offset:64
	s_nop 0
	global_load_dwordx2 v[156:157], v[156:157], off offset:96
	s_waitcnt vmcnt(0)
	v_lshlrev_b32_e32 v139, 16, v166
	v_mul_f32_e32 v141, 0xbfb8aa3b, v139
	v_exp_f32_e32 v141, v141
	v_pk_add_f32 v[212:213], v[2:3], v[126:127]
	v_pk_add_f32 v[172:173], v[4:5], v[128:129]
	v_or_b32_e32 v138, s46, v0
	v_add_f32_e32 v141, 1.0, v141
	v_rcp_f32_e32 v141, v141
	v_pk_add_f32 v[198:199], v[10:11], v[118:119]
	v_mul_f32_e32 v139, v141, v139
	v_and_b32_e32 v141, 0xffff0000, v166
	v_mul_f32_e32 v145, 0xbfb8aa3b, v141
	v_exp_f32_e32 v145, v145
	v_mul_f32_e32 v139, v139, v212
	v_add_f32_e32 v145, 1.0, v145
	v_rcp_f32_e32 v145, v145
	s_nop 0
	v_mul_f32_e32 v141, v145, v141
	v_mul_f32_e32 v141, v141, v213
	v_cvt_pk_bf16_f32 v212, v139, v141
	v_lshlrev_b32_e32 v139, 16, v167
	v_mul_f32_e32 v141, 0xbfb8aa3b, v139
	v_exp_f32_e32 v141, v141
	s_nop 0
	v_add_f32_e32 v141, 1.0, v141
	v_rcp_f32_e32 v141, v141
	s_nop 0
	v_mul_f32_e32 v139, v141, v139
	v_and_b32_e32 v141, 0xffff0000, v167
	v_mul_f32_e32 v145, 0xbfb8aa3b, v141
	v_exp_f32_e32 v145, v145
	v_mul_f32_e32 v139, v139, v172
	v_mov_b64_e32 v[166:167], s[88:89]
	v_mad_u64_u32 v[214:215], s[14:15], v170, s4, v[166:167]
	v_add_f32_e32 v145, 1.0, v145
	v_rcp_f32_e32 v145, v145
	v_mov_b32_e32 v170, v215
	v_mad_u64_u32 v[170:171], s[14:15], v171, s4, v[170:171]
	v_mul_f32_e32 v141, v145, v141
	v_mul_f32_e32 v141, v141, v173
	v_cvt_pk_bf16_f32 v213, v139, v141
	v_lshlrev_b32_e32 v141, 16, v142
	v_mul_f32_e32 v145, 0xbfb8aa3b, v141
	v_exp_f32_e32 v145, v145
	v_and_b32_e32 v142, 0xffff0000, v142
	v_ashrrev_i32_e32 v139, 31, v138
	v_mov_b32_e32 v215, v170
	v_add_f32_e32 v145, 1.0, v145
	v_rcp_f32_e32 v145, v145
	v_lshlrev_b64 v[170:171], 1, v[138:139]
	v_lshl_add_u64 v[172:173], v[214:215], 0, v[170:171]
	global_store_dwordx2 v[172:173], v[212:213], off
	v_mul_f32_e32 v141, v145, v141
	v_mul_f32_e32 v145, 0xbfb8aa3b, v142
	v_exp_f32_e32 v145, v145
	v_pk_add_f32 v[212:213], v[6:7], v[122:123]
	v_pk_add_f32 v[172:173], v[8:9], v[124:125]
	v_mul_f32_e32 v141, v141, v212
	v_add_f32_e32 v145, 1.0, v145
	v_rcp_f32_e32 v145, v145
	s_nop 0
	v_mul_f32_e32 v142, v145, v142
	v_mul_f32_e32 v142, v142, v213
	v_cvt_pk_bf16_f32 v212, v141, v142
	v_lshlrev_b32_e32 v141, 16, v143
	v_mul_f32_e32 v142, 0xbfb8aa3b, v141
	v_exp_f32_e32 v142, v142
	s_nop 0
	v_add_f32_e32 v142, 1.0, v142
	v_rcp_f32_e32 v142, v142
	s_nop 0
	v_mul_f32_e32 v141, v142, v141
	v_and_b32_e32 v142, 0xffff0000, v143
	v_mul_f32_e32 v143, 0xbfb8aa3b, v142
	v_exp_f32_e32 v143, v143
	v_mul_f32_e32 v141, v141, v172
	v_add_f32_e32 v143, 1.0, v143
	v_rcp_f32_e32 v143, v143
	s_nop 0
	v_mul_f32_e32 v142, v143, v142
	v_mul_f32_e32 v142, v142, v173
	v_cvt_pk_bf16_f32 v213, v141, v142
	v_lshl_add_u64 v[142:143], v[0:1], 0, s[46:47]
	v_lshlrev_b32_e32 v0, 16, v194
	v_mul_f32_e32 v141, 0xbfb8aa3b, v0
	v_exp_f32_e32 v141, v141
	v_lshlrev_b64 v[172:173], 1, v[142:143]
	v_lshl_add_u64 v[214:215], v[214:215], 0, v[172:173]
	global_store_dwordx2 v[214:215], v[212:213], off offset:32
	v_add_f32_e32 v141, 1.0, v141
	v_rcp_f32_e32 v141, v141
	v_pk_add_f32 v[212:213], v[12:13], v[120:121]
	v_mul_f32_e32 v0, v141, v0
	v_and_b32_e32 v141, 0xffff0000, v194
	v_mul_f32_e32 v145, 0xbfb8aa3b, v141
	v_exp_f32_e32 v145, v145
	v_mul_f32_e32 v0, v0, v198
	v_add_f32_e32 v145, 1.0, v145
	v_rcp_f32_e32 v145, v145
	s_nop 0
	v_mul_f32_e32 v141, v145, v141
	v_mul_f32_e32 v141, v141, v199
	v_cvt_pk_bf16_f32 v194, v0, v141
	v_lshlrev_b32_e32 v0, 16, v195
	v_mul_f32_e32 v141, 0xbfb8aa3b, v0
	v_exp_f32_e32 v141, v141
	v_pk_add_f32 v[198:199], v[14:15], v[114:115]
	v_add_f32_e32 v141, 1.0, v141
	v_rcp_f32_e32 v141, v141
	s_nop 0
	v_mul_f32_e32 v0, v141, v0
	v_and_b32_e32 v141, 0xffff0000, v195
	v_mul_f32_e32 v145, 0xbfb8aa3b, v141
	v_exp_f32_e32 v145, v145
	v_mul_f32_e32 v0, v0, v212
	v_add_f32_e32 v145, 1.0, v145
	v_rcp_f32_e32 v145, v145
	s_nop 0
	v_mul_f32_e32 v141, v145, v141
	v_mul_f32_e32 v141, v141, v213
	v_cvt_pk_bf16_f32 v195, v0, v141
	v_lshlrev_b32_e32 v0, 16, v192
	v_mul_f32_e32 v141, 0xbfb8aa3b, v0
	v_exp_f32_e32 v141, v141
	global_store_dwordx2 v[214:215], v[194:195], off offset:64
	v_pk_add_f32 v[194:195], v[16:17], v[116:117]
	v_add_f32_e32 v141, 1.0, v141
	v_rcp_f32_e32 v141, v141
	s_nop 0
	v_mul_f32_e32 v0, v141, v0
	v_and_b32_e32 v141, 0xffff0000, v192
	v_mul_f32_e32 v145, 0xbfb8aa3b, v141
	v_exp_f32_e32 v145, v145
	v_mul_f32_e32 v0, v0, v198
	v_add_f32_e32 v145, 1.0, v145
	v_rcp_f32_e32 v145, v145
	s_nop 0
	v_mul_f32_e32 v141, v145, v141
	v_mul_f32_e32 v141, v141, v199
	v_cvt_pk_bf16_f32 v192, v0, v141
	v_lshlrev_b32_e32 v0, 16, v193
	v_mul_f32_e32 v141, 0xbfb8aa3b, v0
	v_exp_f32_e32 v141, v141
	s_nop 0
	v_add_f32_e32 v141, 1.0, v141
	v_rcp_f32_e32 v141, v141
	s_nop 0
	v_mul_f32_e32 v0, v141, v0
	v_and_b32_e32 v141, 0xffff0000, v193
	v_mul_f32_e32 v145, 0xbfb8aa3b, v141
	v_exp_f32_e32 v145, v145
	v_mul_f32_e32 v0, v0, v194
	v_add_f32_e32 v145, 1.0, v145
	v_rcp_f32_e32 v145, v145
	s_nop 0
	v_mul_f32_e32 v141, v145, v141
	v_mul_f32_e32 v141, v141, v195
	v_cvt_pk_bf16_f32 v193, v0, v141
	v_lshlrev_b32_e32 v0, 16, v190
	v_mul_f32_e32 v141, 0xbfb8aa3b, v0
	v_exp_f32_e32 v141, v141
	v_pk_add_f32 v[194:195], v[18:19], v[110:111]
	global_store_dwordx2 v[214:215], v[192:193], off offset:96
	v_pk_add_f32 v[192:193], v[20:21], v[112:113]
	v_add_f32_e32 v141, 1.0, v141
	v_rcp_f32_e32 v141, v141
	s_nop 0
	v_mul_f32_e32 v0, v141, v0
	v_and_b32_e32 v141, 0xffff0000, v190
	v_mul_f32_e32 v145, 0xbfb8aa3b, v141
	v_exp_f32_e32 v145, v145
	v_mul_f32_e32 v0, v0, v194
	v_add_f32_e32 v145, 1.0, v145
	v_rcp_f32_e32 v145, v145
	s_nop 0
	v_mul_f32_e32 v141, v145, v141
	v_mul_f32_e32 v141, v141, v195
	v_cvt_pk_bf16_f32 v190, v0, v141
	v_lshlrev_b32_e32 v0, 16, v191
	v_mul_f32_e32 v141, 0xbfb8aa3b, v0
	v_exp_f32_e32 v141, v141
	s_nop 0
	v_add_f32_e32 v141, 1.0, v141
	v_rcp_f32_e32 v141, v141
	s_nop 0
	v_mul_f32_e32 v0, v141, v0
	v_and_b32_e32 v141, 0xffff0000, v191
	v_mul_f32_e32 v145, 0xbfb8aa3b, v141
	v_exp_f32_e32 v145, v145
	v_mul_f32_e32 v0, v0, v192
	v_add_f32_e32 v145, 1.0, v145
	v_rcp_f32_e32 v145, v145
	s_nop 0
	v_mul_f32_e32 v141, v145, v141
	v_mul_f32_e32 v141, v141, v193
	v_mad_u64_u32 v[192:193], s[14:15], v188, s4, v[166:167]
	v_cvt_pk_bf16_f32 v191, v0, v141
	v_mov_b32_e32 v0, v193
	v_mad_u64_u32 v[188:189], s[14:15], v189, s4, v[0:1]
	v_lshlrev_b32_e32 v0, 16, v186
	v_mul_f32_e32 v141, 0xbfb8aa3b, v0
	v_exp_f32_e32 v141, v141
	v_mov_b32_e32 v193, v188
	v_lshl_add_u64 v[188:189], v[192:193], 0, v[170:171]
	global_store_dwordx2 v[188:189], v[190:191], off
	v_add_f32_e32 v141, 1.0, v141
	v_rcp_f32_e32 v141, v141
	v_pk_add_f32 v[190:191], v[22:23], v[106:107]
	v_pk_add_f32 v[188:189], v[24:25], v[108:109]
	v_mul_f32_e32 v0, v141, v0
	v_and_b32_e32 v141, 0xffff0000, v186
	v_mul_f32_e32 v145, 0xbfb8aa3b, v141
	v_exp_f32_e32 v145, v145
	v_mul_f32_e32 v0, v0, v190
	v_add_f32_e32 v145, 1.0, v145
	v_rcp_f32_e32 v145, v145
	s_nop 0
	v_mul_f32_e32 v141, v145, v141
	v_mul_f32_e32 v141, v141, v191
	v_cvt_pk_bf16_f32 v186, v0, v141
	v_lshlrev_b32_e32 v0, 16, v187
	v_mul_f32_e32 v141, 0xbfb8aa3b, v0
	v_exp_f32_e32 v141, v141
	v_pk_add_f32 v[190:191], v[26:27], v[102:103]
	v_add_f32_e32 v141, 1.0, v141
	v_rcp_f32_e32 v141, v141
	s_nop 0
	v_mul_f32_e32 v0, v141, v0
	v_and_b32_e32 v141, 0xffff0000, v187
	v_mul_f32_e32 v145, 0xbfb8aa3b, v141
	v_exp_f32_e32 v145, v145
	v_mul_f32_e32 v0, v0, v188
	v_add_f32_e32 v145, 1.0, v145
	v_rcp_f32_e32 v145, v145
	s_nop 0
	v_mul_f32_e32 v141, v145, v141
	v_mul_f32_e32 v141, v141, v189
	v_cvt_pk_bf16_f32 v187, v0, v141
	v_lshlrev_b32_e32 v0, 16, v184
	v_mul_f32_e32 v141, 0xbfb8aa3b, v0
	v_exp_f32_e32 v141, v141
	v_lshl_add_u64 v[188:189], v[192:193], 0, v[172:173]
	global_store_dwordx2 v[188:189], v[186:187], off offset:32
	v_pk_add_f32 v[186:187], v[28:29], v[104:105]
	v_add_f32_e32 v141, 1.0, v141
	v_rcp_f32_e32 v141, v141
	s_nop 0
	v_mul_f32_e32 v0, v141, v0
	v_and_b32_e32 v141, 0xffff0000, v184
	v_mul_f32_e32 v145, 0xbfb8aa3b, v141
	v_exp_f32_e32 v145, v145
	v_mul_f32_e32 v0, v0, v190
	v_add_f32_e32 v145, 1.0, v145
	v_rcp_f32_e32 v145, v145
	s_nop 0
	v_mul_f32_e32 v141, v145, v141
	v_mul_f32_e32 v141, v141, v191
	v_cvt_pk_bf16_f32 v184, v0, v141
	v_lshlrev_b32_e32 v0, 16, v185
	v_mul_f32_e32 v141, 0xbfb8aa3b, v0
	v_exp_f32_e32 v141, v141
	s_nop 0
	v_add_f32_e32 v141, 1.0, v141
	v_rcp_f32_e32 v141, v141
	s_nop 0
	v_mul_f32_e32 v0, v141, v0
	v_and_b32_e32 v141, 0xffff0000, v185
	v_mul_f32_e32 v145, 0xbfb8aa3b, v141
	v_exp_f32_e32 v145, v145
	v_mul_f32_e32 v0, v0, v186
	v_add_f32_e32 v145, 1.0, v145
	v_rcp_f32_e32 v145, v145
	s_nop 0
	v_mul_f32_e32 v141, v145, v141
	v_mul_f32_e32 v141, v141, v187
	v_cvt_pk_bf16_f32 v185, v0, v141
	v_lshlrev_b32_e32 v0, 16, v182
	v_mul_f32_e32 v141, 0xbfb8aa3b, v0
	v_exp_f32_e32 v141, v141
	v_pk_add_f32 v[186:187], v[30:31], v[98:99]
	global_store_dwordx2 v[188:189], v[184:185], off offset:64
	v_pk_add_f32 v[184:185], v[32:33], v[100:101]
	v_add_f32_e32 v141, 1.0, v141
	v_rcp_f32_e32 v141, v141
	s_nop 0
	v_mul_f32_e32 v0, v141, v0
	v_and_b32_e32 v141, 0xffff0000, v182
	v_mul_f32_e32 v145, 0xbfb8aa3b, v141
	v_exp_f32_e32 v145, v145
	v_mul_f32_e32 v0, v0, v186
	v_add_f32_e32 v145, 1.0, v145
	v_rcp_f32_e32 v145, v145
	s_nop 0
	v_mul_f32_e32 v141, v145, v141
	v_mul_f32_e32 v141, v141, v187
	v_cvt_pk_bf16_f32 v182, v0, v141
	v_lshlrev_b32_e32 v0, 16, v183
	v_mul_f32_e32 v141, 0xbfb8aa3b, v0
	v_exp_f32_e32 v141, v141
	s_nop 0
	v_add_f32_e32 v141, 1.0, v141
	v_rcp_f32_e32 v141, v141
	s_nop 0
	v_mul_f32_e32 v0, v141, v0
	v_and_b32_e32 v141, 0xffff0000, v183
	v_mul_f32_e32 v145, 0xbfb8aa3b, v141
	v_exp_f32_e32 v145, v145
	v_mul_f32_e32 v0, v0, v184
	v_add_f32_e32 v145, 1.0, v145
	v_rcp_f32_e32 v145, v145
	s_nop 0
	v_mul_f32_e32 v141, v145, v141
	v_mul_f32_e32 v141, v141, v185
	v_cvt_pk_bf16_f32 v183, v0, v141
	v_lshlrev_b32_e32 v0, 16, v180
	v_mul_f32_e32 v141, 0xbfb8aa3b, v0
	v_exp_f32_e32 v141, v141
	v_pk_add_f32 v[184:185], v[34:35], v[94:95]
	global_store_dwordx2 v[188:189], v[182:183], off offset:96
	v_pk_add_f32 v[182:183], v[36:37], v[96:97]
	v_add_f32_e32 v141, 1.0, v141
	v_rcp_f32_e32 v141, v141
	s_nop 0
	v_mul_f32_e32 v0, v141, v0
	v_and_b32_e32 v141, 0xffff0000, v180
	v_mul_f32_e32 v145, 0xbfb8aa3b, v141
	v_exp_f32_e32 v145, v145
	v_mul_f32_e32 v0, v0, v184
	v_add_f32_e32 v145, 1.0, v145
	v_rcp_f32_e32 v145, v145
	s_nop 0
	v_mul_f32_e32 v141, v145, v141
	v_mul_f32_e32 v141, v141, v185
	v_cvt_pk_bf16_f32 v180, v0, v141
	v_lshlrev_b32_e32 v0, 16, v181
	v_mul_f32_e32 v141, 0xbfb8aa3b, v0
	v_exp_f32_e32 v141, v141
	s_nop 0
	v_add_f32_e32 v141, 1.0, v141
	v_rcp_f32_e32 v141, v141
	s_nop 0
	v_mul_f32_e32 v0, v141, v0
	v_and_b32_e32 v141, 0xffff0000, v181
	v_mul_f32_e32 v145, 0xbfb8aa3b, v141
	v_exp_f32_e32 v145, v145
	v_mul_f32_e32 v0, v0, v182
	v_add_f32_e32 v145, 1.0, v145
	v_rcp_f32_e32 v145, v145
	s_nop 0
	v_mul_f32_e32 v141, v145, v141
	v_mul_f32_e32 v141, v141, v183
	v_mad_u64_u32 v[182:183], s[14:15], v178, s4, v[166:167]
	v_cvt_pk_bf16_f32 v181, v0, v141
	v_mov_b32_e32 v0, v183
	v_mad_u64_u32 v[178:179], s[14:15], v179, s4, v[0:1]
	v_lshlrev_b32_e32 v0, 16, v176
	v_mul_f32_e32 v141, 0xbfb8aa3b, v0
	v_exp_f32_e32 v141, v141
	v_mov_b32_e32 v183, v178
	v_lshl_add_u64 v[178:179], v[182:183], 0, v[170:171]
	global_store_dwordx2 v[178:179], v[180:181], off
	v_add_f32_e32 v141, 1.0, v141
	v_rcp_f32_e32 v141, v141
	v_pk_add_f32 v[180:181], v[38:39], v[90:91]
	v_pk_add_f32 v[178:179], v[40:41], v[92:93]
	v_mad_u64_u32 v[166:167], s[14:15], v162, s4, v[166:167]
	v_mul_f32_e32 v0, v141, v0
	v_and_b32_e32 v141, 0xffff0000, v176
	v_mul_f32_e32 v145, 0xbfb8aa3b, v141
	v_exp_f32_e32 v145, v145
	v_mul_f32_e32 v0, v0, v180
	v_add_f32_e32 v145, 1.0, v145
	v_rcp_f32_e32 v145, v145
	s_nop 0
	v_mul_f32_e32 v141, v145, v141
	v_mul_f32_e32 v141, v141, v181
	v_cvt_pk_bf16_f32 v176, v0, v141
	v_lshlrev_b32_e32 v0, 16, v177
	v_mul_f32_e32 v141, 0xbfb8aa3b, v0
	v_exp_f32_e32 v141, v141
	v_pk_add_f32 v[180:181], v[42:43], v[86:87]
	v_add_f32_e32 v141, 1.0, v141
	v_rcp_f32_e32 v141, v141
	s_nop 0
	v_mul_f32_e32 v0, v141, v0
	v_and_b32_e32 v141, 0xffff0000, v177
	v_mul_f32_e32 v145, 0xbfb8aa3b, v141
	v_exp_f32_e32 v145, v145
	v_mul_f32_e32 v0, v0, v178
	v_add_f32_e32 v145, 1.0, v145
	v_rcp_f32_e32 v145, v145
	s_nop 0
	v_mul_f32_e32 v141, v145, v141
	v_mul_f32_e32 v141, v141, v179
	v_cvt_pk_bf16_f32 v177, v0, v141
	v_lshlrev_b32_e32 v0, 16, v174
	v_mul_f32_e32 v141, 0xbfb8aa3b, v0
	v_exp_f32_e32 v141, v141
	v_lshl_add_u64 v[178:179], v[182:183], 0, v[172:173]
	global_store_dwordx2 v[178:179], v[176:177], off offset:32
	v_pk_add_f32 v[176:177], v[44:45], v[88:89]
	v_add_f32_e32 v141, 1.0, v141
	v_rcp_f32_e32 v141, v141
	s_nop 0
	v_mul_f32_e32 v0, v141, v0
	v_and_b32_e32 v141, 0xffff0000, v174
	v_mul_f32_e32 v145, 0xbfb8aa3b, v141
	v_exp_f32_e32 v145, v145
	v_mul_f32_e32 v0, v0, v180
	v_add_f32_e32 v145, 1.0, v145
	v_rcp_f32_e32 v145, v145
	s_nop 0
	v_mul_f32_e32 v141, v145, v141
	v_mul_f32_e32 v141, v141, v181
	v_cvt_pk_bf16_f32 v174, v0, v141
	v_lshlrev_b32_e32 v0, 16, v175
	v_mul_f32_e32 v141, 0xbfb8aa3b, v0
	v_exp_f32_e32 v141, v141
	s_nop 0
	v_add_f32_e32 v141, 1.0, v141
	v_rcp_f32_e32 v141, v141
	s_nop 0
	v_mul_f32_e32 v0, v141, v0
	v_and_b32_e32 v141, 0xffff0000, v175
	v_mul_f32_e32 v145, 0xbfb8aa3b, v141
	v_exp_f32_e32 v145, v145
	v_mul_f32_e32 v0, v0, v176
	v_add_f32_e32 v145, 1.0, v145
	v_rcp_f32_e32 v145, v145
	s_nop 0
	v_mul_f32_e32 v141, v145, v141
	v_mul_f32_e32 v141, v141, v177
	v_cvt_pk_bf16_f32 v175, v0, v141
	v_lshlrev_b32_e32 v0, 16, v168
	v_mul_f32_e32 v141, 0xbfb8aa3b, v0
	v_exp_f32_e32 v141, v141
	v_pk_add_f32 v[176:177], v[46:47], v[82:83]
	global_store_dwordx2 v[178:179], v[174:175], off offset:64
	v_pk_add_f32 v[174:175], v[48:49], v[84:85]
	v_add_f32_e32 v141, 1.0, v141
	v_rcp_f32_e32 v141, v141
	s_nop 0
	v_mul_f32_e32 v0, v141, v0
	v_and_b32_e32 v141, 0xffff0000, v168
	v_mul_f32_e32 v145, 0xbfb8aa3b, v141
	v_exp_f32_e32 v145, v145
	v_mul_f32_e32 v0, v0, v176
	v_add_f32_e32 v145, 1.0, v145
	v_rcp_f32_e32 v145, v145
	s_nop 0
	v_mul_f32_e32 v141, v145, v141
	v_mul_f32_e32 v141, v141, v177
	v_cvt_pk_bf16_f32 v168, v0, v141
	v_lshlrev_b32_e32 v0, 16, v169
	v_mul_f32_e32 v141, 0xbfb8aa3b, v0
	v_exp_f32_e32 v141, v141
	s_nop 0
	v_add_f32_e32 v141, 1.0, v141
	v_rcp_f32_e32 v141, v141
	s_nop 0
	v_mul_f32_e32 v0, v141, v0
	v_and_b32_e32 v141, 0xffff0000, v169
	v_mul_f32_e32 v145, 0xbfb8aa3b, v141
	v_exp_f32_e32 v145, v145
	v_mul_f32_e32 v0, v0, v174
	v_add_f32_e32 v145, 1.0, v145
	v_rcp_f32_e32 v145, v145
	s_nop 0
	v_mul_f32_e32 v141, v145, v141
	v_mul_f32_e32 v141, v141, v175
	v_cvt_pk_bf16_f32 v169, v0, v141
	v_lshlrev_b32_e32 v0, 16, v164
	v_mul_f32_e32 v141, 0xbfb8aa3b, v0
	v_exp_f32_e32 v141, v141
	v_pk_add_f32 v[174:175], v[50:51], v[78:79]
	global_store_dwordx2 v[178:179], v[168:169], off offset:96
	v_pk_add_f32 v[168:169], v[52:53], v[80:81]
	v_add_f32_e32 v141, 1.0, v141
	v_rcp_f32_e32 v141, v141
	s_nop 0
	v_mul_f32_e32 v0, v141, v0
	v_and_b32_e32 v141, 0xffff0000, v164
	v_mul_f32_e32 v145, 0xbfb8aa3b, v141
	v_exp_f32_e32 v145, v145
	v_mul_f32_e32 v0, v0, v174
	v_add_f32_e32 v145, 1.0, v145
	v_rcp_f32_e32 v145, v145
	s_nop 0
	v_mul_f32_e32 v141, v145, v141
	v_mul_f32_e32 v141, v141, v175
	v_cvt_pk_bf16_f32 v164, v0, v141
	v_lshlrev_b32_e32 v0, 16, v165
	v_mul_f32_e32 v141, 0xbfb8aa3b, v0
	v_exp_f32_e32 v141, v141
	s_nop 0
	v_add_f32_e32 v141, 1.0, v141
	v_rcp_f32_e32 v141, v141
	s_nop 0
	v_mul_f32_e32 v0, v141, v0
	v_and_b32_e32 v141, 0xffff0000, v165
	v_mul_f32_e32 v145, 0xbfb8aa3b, v141
	v_exp_f32_e32 v145, v145
	v_mul_f32_e32 v0, v0, v168
	v_add_f32_e32 v145, 1.0, v145
	v_rcp_f32_e32 v145, v145
	s_nop 0
	v_mul_f32_e32 v141, v145, v141
	v_mul_f32_e32 v141, v141, v169
	v_cvt_pk_bf16_f32 v165, v0, v141
	v_mov_b32_e32 v0, v167
	v_mad_u64_u32 v[162:163], s[14:15], v163, s4, v[0:1]
	v_lshlrev_b32_e32 v0, 16, v160
	v_mul_f32_e32 v141, 0xbfb8aa3b, v0
	v_exp_f32_e32 v141, v141
	v_mov_b32_e32 v167, v162
	v_lshl_add_u64 v[162:163], v[166:167], 0, v[170:171]
	global_store_dwordx2 v[162:163], v[164:165], off
	v_add_f32_e32 v141, 1.0, v141
	v_rcp_f32_e32 v141, v141
	v_pk_add_f32 v[164:165], v[54:55], v[74:75]
	v_pk_add_f32 v[162:163], v[56:57], v[76:77]
	v_mul_f32_e32 v0, v141, v0
	v_and_b32_e32 v141, 0xffff0000, v160
	v_mul_f32_e32 v145, 0xbfb8aa3b, v141
	v_exp_f32_e32 v145, v145
	v_mul_f32_e32 v0, v0, v164
	v_add_f32_e32 v145, 1.0, v145
	v_rcp_f32_e32 v145, v145
	s_nop 0
	v_mul_f32_e32 v141, v145, v141
	v_mul_f32_e32 v141, v141, v165
	v_cvt_pk_bf16_f32 v160, v0, v141
	v_lshlrev_b32_e32 v0, 16, v161
	v_mul_f32_e32 v141, 0xbfb8aa3b, v0
	v_exp_f32_e32 v141, v141
	v_pk_add_f32 v[164:165], v[58:59], v[70:71]
	v_add_f32_e32 v141, 1.0, v141
	v_rcp_f32_e32 v141, v141
	s_nop 0
	v_mul_f32_e32 v0, v141, v0
	v_and_b32_e32 v141, 0xffff0000, v161
	v_mul_f32_e32 v145, 0xbfb8aa3b, v141
	v_exp_f32_e32 v145, v145
	v_mul_f32_e32 v0, v0, v162
	v_add_f32_e32 v145, 1.0, v145
	v_rcp_f32_e32 v145, v145
	s_nop 0
	v_mul_f32_e32 v141, v145, v141
	v_mul_f32_e32 v141, v141, v163
	v_cvt_pk_bf16_f32 v161, v0, v141
	v_lshlrev_b32_e32 v0, 16, v158
	v_mul_f32_e32 v141, 0xbfb8aa3b, v0
	v_exp_f32_e32 v141, v141
	v_lshl_add_u64 v[162:163], v[166:167], 0, v[172:173]
	global_store_dwordx2 v[162:163], v[160:161], off offset:32
	v_pk_add_f32 v[160:161], v[60:61], v[72:73]
	v_add_f32_e32 v141, 1.0, v141
	v_rcp_f32_e32 v141, v141
	s_nop 0
	v_mul_f32_e32 v0, v141, v0
	v_and_b32_e32 v141, 0xffff0000, v158
	v_mul_f32_e32 v145, 0xbfb8aa3b, v141
	v_exp_f32_e32 v145, v145
	v_mul_f32_e32 v0, v0, v164
	v_add_f32_e32 v145, 1.0, v145
	v_rcp_f32_e32 v145, v145
	s_nop 0
	v_mul_f32_e32 v141, v145, v141
	v_mul_f32_e32 v141, v141, v165
	v_cvt_pk_bf16_f32 v158, v0, v141
	v_lshlrev_b32_e32 v0, 16, v159
	v_mul_f32_e32 v141, 0xbfb8aa3b, v0
	v_exp_f32_e32 v141, v141
	s_nop 0
	v_add_f32_e32 v141, 1.0, v141
	v_rcp_f32_e32 v141, v141
	s_nop 0
	v_mul_f32_e32 v0, v141, v0
	v_and_b32_e32 v141, 0xffff0000, v159
	v_mul_f32_e32 v145, 0xbfb8aa3b, v141
	v_exp_f32_e32 v145, v145
	v_mul_f32_e32 v0, v0, v160
	v_add_f32_e32 v145, 1.0, v145
	v_rcp_f32_e32 v145, v145
	s_nop 0
	v_mul_f32_e32 v141, v145, v141
	v_mul_f32_e32 v141, v141, v161
	v_cvt_pk_bf16_f32 v159, v0, v141
	v_lshlrev_b32_e32 v0, 16, v156
	v_mul_f32_e32 v141, 0xbfb8aa3b, v0
	v_exp_f32_e32 v141, v141
	v_pk_add_f32 v[160:161], v[62:63], v[66:67]
	global_store_dwordx2 v[162:163], v[158:159], off offset:64
	v_pk_add_f32 v[158:159], v[64:65], v[68:69]
	v_add_f32_e32 v141, 1.0, v141
	v_rcp_f32_e32 v141, v141
	s_nop 0
	v_mul_f32_e32 v0, v141, v0
	v_and_b32_e32 v141, 0xffff0000, v156
	v_mul_f32_e32 v145, 0xbfb8aa3b, v141
	v_exp_f32_e32 v145, v145
	v_mul_f32_e32 v0, v0, v160
	v_add_f32_e32 v145, 1.0, v145
	v_rcp_f32_e32 v145, v145
	s_nop 0
	v_mul_f32_e32 v141, v145, v141
	v_mul_f32_e32 v141, v141, v161
	v_cvt_pk_bf16_f32 v156, v0, v141
	v_lshlrev_b32_e32 v0, 16, v157
	v_mul_f32_e32 v141, 0xbfb8aa3b, v0
	v_exp_f32_e32 v141, v141
	s_nop 0
	v_add_f32_e32 v141, 1.0, v141
	v_rcp_f32_e32 v141, v141
	s_nop 0
	v_mul_f32_e32 v0, v141, v0
	v_and_b32_e32 v141, 0xffff0000, v157
	v_mul_f32_e32 v145, 0xbfb8aa3b, v141
	v_exp_f32_e32 v145, v145
	v_mul_f32_e32 v0, v0, v158
	v_add_f32_e32 v145, 1.0, v145
	v_rcp_f32_e32 v145, v145
	s_nop 0
	v_mul_f32_e32 v141, v145, v141
	v_mul_f32_e32 v141, v141, v159
	v_cvt_pk_bf16_f32 v157, v0, v141
	global_store_dwordx2 v[162:163], v[156:157], off offset:96
	v_mul_lo_u32 v0, v248, s23
	v_or_b32_e32 v141, s11, v247
	v_sub_u32_e32 v0, v0, v141
	v_and_b32_e32 v141, 0xfff, v0
	v_or_b32_e32 v141, s40, v141
	v_mad_u64_u32 v[156:157], s[14:15], v141, s90, v[152:153]
	v_mad_i32_i24 v157, s41, v220, v157
	v_lshl_add_u64 v[156:157], v[156:157], 0, s[6:7]
	v_lshl_add_u64 v[156:157], v[156:157], 0, v[154:155]
	v_add_u32_e32 v141, 0xff0, v0
	v_lshl_add_u64 v[158:159], v[156:157], 0, s[94:95]
	v_add_co_u32_e32 v156, vcc, s10, v156
	v_and_b32_e32 v141, 0xfff, v141
	s_nop 0
	v_addc_co_u32_e32 v157, vcc, 0, v157, vcc
	v_or_b32_e32 v141, s40, v141
	global_load_dwordx2 v[182:183], v[156:157], off offset:1024
	global_load_dwordx2 v[180:181], v[158:159], off offset:32
	global_load_dwordx2 v[178:179], v[158:159], off offset:64
	global_load_dwordx2 v[176:177], v[158:159], off offset:96
	v_mad_u64_u32 v[156:157], s[14:15], v141, s90, v[152:153]
	v_mad_i32_i24 v157, s41, v220, v157
	v_lshl_add_u64 v[156:157], v[156:157], 0, s[6:7]
	v_lshl_add_u64 v[156:157], v[156:157], 0, v[154:155]
	v_add_u32_e32 v141, 0xfe0, v0
	v_lshl_add_u64 v[158:159], v[156:157], 0, s[94:95]
	v_add_co_u32_e32 v156, vcc, s10, v156
	v_and_b32_e32 v141, 0xfff, v141
	s_nop 0
	v_addc_co_u32_e32 v157, vcc, 0, v157, vcc
	v_or_b32_e32 v141, s40, v141
	v_add_u32_e32 v0, 0xfd0, v0
	global_load_dwordx2 v[174:175], v[156:157], off offset:1024
	global_load_dwordx2 v[172:173], v[158:159], off offset:32
	global_load_dwordx2 v[170:171], v[158:159], off offset:64
	global_load_dwordx2 v[168:169], v[158:159], off offset:96
	v_mad_u64_u32 v[156:157], s[14:15], v141, s90, v[152:153]
	v_and_b32_e32 v0, 0xfff, v0
	v_mad_i32_i24 v157, s41, v220, v157
	v_or_b32_e32 v0, s40, v0
	v_lshl_add_u64 v[156:157], v[156:157], 0, s[6:7]
	v_mad_u64_u32 v[152:153], s[14:15], v0, s90, v[152:153]
	v_lshl_add_u64 v[156:157], v[156:157], 0, v[154:155]
	v_mad_i32_i24 v153, s41, v220, v153
	v_lshl_add_u64 v[158:159], v[156:157], 0, s[94:95]
	v_add_co_u32_e32 v156, vcc, s10, v156
	v_lshl_add_u64 v[152:153], v[152:153], 0, s[6:7]
	s_nop 0
	v_addc_co_u32_e32 v157, vcc, 0, v157, vcc
	v_lshl_add_u64 v[152:153], v[152:153], 0, v[154:155]
	v_lshl_add_u64 v[184:185], v[152:153], 0, s[94:95]
	v_add_co_u32_e32 v152, vcc, 0x114ed000, v152
	global_load_dwordx2 v[166:167], v[156:157], off offset:1024
	global_load_dwordx2 v[164:165], v[158:159], off offset:32
	global_load_dwordx2 v[162:163], v[158:159], off offset:64
	global_load_dwordx2 v[160:161], v[158:159], off offset:96
	v_addc_co_u32_e32 v153, vcc, 0, v153, vcc
	global_load_dwordx2 v[158:159], v[152:153], off offset:1024
	global_load_dwordx2 v[156:157], v[184:185], off offset:32
	global_load_dwordx2 v[154:155], v[184:185], off offset:64
	s_nop 0
	global_load_dwordx2 v[152:153], v[184:185], off offset:96
	v_add_u32_e32 v0, s11, v148
	v_cmp_lt_i32_e32 vcc, 0, v0
	s_and_saveexec_b64 s[6:7], vcc
	s_cbranch_execz .LBB0_851
	s_waitcnt vmcnt(15)
	v_lshlrev_b32_e32 v184, 16, v182
	v_sub_u32_e32 v148, 0x1000, v0
	v_mul_f32_e32 v0, 0xbfb8aa3b, v184
	v_exp_f32_e32 v0, v0
	v_and_b32_e32 v185, 0xffff0000, v182
	v_lshlrev_b32_e32 v182, 16, v183
	v_sub_f32_e32 v127, v3, v127
	v_add_f32_e32 v0, 1.0, v0
	v_rcp_f32_e32 v186, v0
	v_mul_f32_e32 v0, 0xbfb8aa3b, v185
	v_exp_f32_e32 v0, v0
	v_sub_f32_e32 v126, v2, v126
	v_and_b32_e32 v183, 0xffff0000, v183
	v_sub_f32_e32 v129, v5, v129
	v_add_f32_e32 v0, 1.0, v0
	v_rcp_f32_e32 v187, v0
	v_mul_f32_e32 v0, 0xbfb8aa3b, v182
	v_exp_f32_e32 v0, v0
	v_sub_f32_e32 v128, v4, v128
	v_pk_mul_f32 v[184:185], v[186:187], v[184:185]
	v_ashrrev_i32_e32 v149, 31, v148
	v_add_f32_e32 v0, 1.0, v0
	v_pk_mul_f32 v[126:127], v[184:185], v[126:127]
	v_rcp_f32_e32 v184, v0
	v_mul_f32_e32 v0, 0xbfb8aa3b, v183
	v_exp_f32_e32 v0, v0
	v_lshl_add_u64 v[148:149], s[40:41], 0, v[148:149]
	v_cvt_pk_bf16_f32 v126, v126, v127
	v_sub_f32_e32 v123, v7, v123
	v_add_f32_e32 v0, 1.0, v0
	v_rcp_f32_e32 v185, v0
	v_sub_f32_e32 v122, v6, v122
	v_sub_f32_e32 v125, v9, v125
	v_sub_f32_e32 v124, v8, v124
	v_pk_mul_f32 v[182:183], v[184:185], v[182:183]
	v_sub_f32_e32 v119, v11, v119
	v_pk_mul_f32 v[128:129], v[182:183], v[128:129]
	v_sub_f32_e32 v118, v10, v118
	v_cvt_pk_bf16_f32 v127, v128, v129
	v_mov_b64_e32 v[128:129], s[88:89]
	v_mad_u64_u32 v[128:129], s[14:15], v148, s4, v[128:129]
	v_mad_i32_i24 v129, v149, s4, v129
	v_lshl_add_u64 v[148:149], v[138:139], 1, v[128:129]
	global_store_dwordx2 v[148:149], v[126:127], off
	s_waitcnt vmcnt(15)
	v_lshlrev_b32_e32 v126, 16, v180
	v_mul_f32_e32 v0, 0xbfb8aa3b, v126
	v_exp_f32_e32 v0, v0
	v_and_b32_e32 v127, 0xffff0000, v180
	v_sub_f32_e32 v121, v13, v121
	v_sub_f32_e32 v120, v12, v120
	v_add_f32_e32 v0, 1.0, v0
	v_rcp_f32_e32 v148, v0
	v_mul_f32_e32 v0, 0xbfb8aa3b, v127
	v_exp_f32_e32 v0, v0
	v_sub_f32_e32 v115, v15, v115
	v_sub_f32_e32 v114, v14, v114
	v_sub_f32_e32 v117, v17, v117
	v_add_f32_e32 v0, 1.0, v0
	v_rcp_f32_e32 v149, v0
	v_sub_f32_e32 v116, v16, v116
	v_pk_mul_f32 v[126:127], v[148:149], v[126:127]
	s_nop 0
	v_pk_mul_f32 v[122:123], v[126:127], v[122:123]
	v_lshlrev_b32_e32 v126, 16, v181
	v_mul_f32_e32 v0, 0xbfb8aa3b, v126
	v_exp_f32_e32 v0, v0
	v_and_b32_e32 v127, 0xffff0000, v181
	v_cvt_pk_bf16_f32 v122, v122, v123
	v_add_f32_e32 v0, 1.0, v0
	v_rcp_f32_e32 v148, v0
	v_mul_f32_e32 v0, 0xbfb8aa3b, v127
	v_exp_f32_e32 v0, v0
	s_nop 0
	v_add_f32_e32 v0, 1.0, v0
	v_rcp_f32_e32 v149, v0
	s_nop 0
	v_pk_mul_f32 v[126:127], v[148:149], v[126:127]
	s_nop 0
	v_pk_mul_f32 v[124:125], v[126:127], v[124:125]
	s_nop 0
	v_cvt_pk_bf16_f32 v123, v124, v125
	v_lshl_add_u64 v[124:125], v[142:143], 1, v[128:129]
	global_store_dwordx2 v[124:125], v[122:123], off offset:32
	s_waitcnt vmcnt(15)
	v_lshlrev_b32_e32 v122, 16, v178
	v_mul_f32_e32 v0, 0xbfb8aa3b, v122
	v_exp_f32_e32 v0, v0
	v_and_b32_e32 v123, 0xffff0000, v178
	v_add_f32_e32 v0, 1.0, v0
	v_rcp_f32_e32 v126, v0
	v_mul_f32_e32 v0, 0xbfb8aa3b, v123
	v_exp_f32_e32 v0, v0
	s_nop 0
	v_add_f32_e32 v0, 1.0, v0
	v_rcp_f32_e32 v127, v0
	s_nop 0
	v_pk_mul_f32 v[122:123], v[126:127], v[122:123]
	s_nop 0
	v_pk_mul_f32 v[118:119], v[122:123], v[118:119]
	v_lshlrev_b32_e32 v122, 16, v179
	v_mul_f32_e32 v0, 0xbfb8aa3b, v122
	v_exp_f32_e32 v0, v0
	v_and_b32_e32 v123, 0xffff0000, v179
	v_cvt_pk_bf16_f32 v118, v118, v119
	v_add_f32_e32 v0, 1.0, v0
	v_rcp_f32_e32 v126, v0
	v_mul_f32_e32 v0, 0xbfb8aa3b, v123
	v_exp_f32_e32 v0, v0
	s_nop 0
	v_add_f32_e32 v0, 1.0, v0
	v_rcp_f32_e32 v127, v0
	s_nop 0
	v_pk_mul_f32 v[122:123], v[126:127], v[122:123]
	s_nop 0
	v_pk_mul_f32 v[120:121], v[122:123], v[120:121]
	s_nop 0
	v_cvt_pk_bf16_f32 v119, v120, v121
	global_store_dwordx2 v[124:125], v[118:119], off offset:64
	s_waitcnt vmcnt(15)
	v_lshlrev_b32_e32 v118, 16, v176
	v_mul_f32_e32 v0, 0xbfb8aa3b, v118
	v_exp_f32_e32 v0, v0
	v_and_b32_e32 v119, 0xffff0000, v176
	v_add_f32_e32 v0, 1.0, v0
	v_rcp_f32_e32 v120, v0
	v_mul_f32_e32 v0, 0xbfb8aa3b, v119
	v_exp_f32_e32 v0, v0
	s_nop 0
	v_add_f32_e32 v0, 1.0, v0
	v_rcp_f32_e32 v121, v0
	s_nop 0
	v_pk_mul_f32 v[118:119], v[120:121], v[118:119]
	s_nop 0
	v_pk_mul_f32 v[114:115], v[118:119], v[114:115]
	v_lshlrev_b32_e32 v118, 16, v177
	v_mul_f32_e32 v0, 0xbfb8aa3b, v118
	v_exp_f32_e32 v0, v0
	v_and_b32_e32 v119, 0xffff0000, v177
	v_cvt_pk_bf16_f32 v114, v114, v115
	v_add_f32_e32 v0, 1.0, v0
	v_rcp_f32_e32 v120, v0
	v_mul_f32_e32 v0, 0xbfb8aa3b, v119
	v_exp_f32_e32 v0, v0
	s_nop 0
	v_add_f32_e32 v0, 1.0, v0
	v_rcp_f32_e32 v121, v0
	s_nop 0
	v_pk_mul_f32 v[118:119], v[120:121], v[118:119]
	s_nop 0
	v_pk_mul_f32 v[116:117], v[118:119], v[116:117]
	s_nop 0
	v_cvt_pk_bf16_f32 v115, v116, v117
	global_store_dwordx2 v[124:125], v[114:115], off offset:96

.LBB0_866:
	v_add_u32_e32 v0, v239, v235
	ds_read_b128 v[138:141], v246
	ds_read_b128 v[146:149], v246 offset:2048
	ds_read_b128 v[142:145], v243
	ds_read_b128 v[160:163], v0
	ds_read_b128 v[152:155], v244
	ds_read_b128 v[156:159], v245
	ds_read_b128 v[164:167], v246 offset:4096
	ds_read_b128 v[168:171], v246 offset:6144
	s_add_i32 s6, s6, 1
	s_cmp_lg_u32 s6, 64
	s_waitcnt lgkmcnt(5)
	v_mfma_f32_16x16x32_bf16 v[126:129], v[138:141], v[142:145], v[126:129]
	v_mfma_f32_16x16x32_bf16 v[122:125], v[146:149], v[142:145], v[122:125]
	s_waitcnt lgkmcnt(4)
	v_mfma_f32_16x16x32_bf16 v[110:113], v[138:141], v[160:163], v[110:113]
	v_mfma_f32_16x16x32_bf16 v[106:109], v[146:149], v[160:163], v[106:109]
	s_waitcnt lgkmcnt(1)
	v_mfma_f32_16x16x32_bf16 v[118:121], v[164:167], v[142:145], v[118:121]
	v_mfma_f32_16x16x32_bf16 v[102:105], v[164:167], v[160:163], v[102:105]
	v_mfma_f32_16x16x32_bf16 v[94:97], v[138:141], v[152:155], v[94:97]
	v_mfma_f32_16x16x32_bf16 v[90:93], v[146:149], v[152:155], v[90:93]
	s_waitcnt lgkmcnt(0)
	v_mfma_f32_16x16x32_bf16 v[114:117], v[168:171], v[142:145], v[114:117]
	v_mfma_f32_16x16x32_bf16 v[98:101], v[168:171], v[160:163], v[98:101]
	v_mfma_f32_16x16x32_bf16 v[86:89], v[164:167], v[152:155], v[86:89]
	v_mfma_f32_16x16x32_bf16 v[82:85], v[168:171], v[152:155], v[82:85]
	v_mfma_f32_16x16x32_bf16 v[78:81], v[138:141], v[156:159], v[78:81]
	v_mfma_f32_16x16x32_bf16 v[74:77], v[146:149], v[156:159], v[74:77]
	v_mfma_f32_16x16x32_bf16 v[70:73], v[164:167], v[156:159], v[70:73]
	v_mfma_f32_16x16x32_bf16 v[66:69], v[168:171], v[156:159], v[66:69]
	ds_read_b128 v[138:141], v246 offset:1024
	ds_read_b128 v[142:145], v246 offset:3072
	ds_read_b128 v[152:155], v246 offset:7168
	ds_read_b128 v[156:159], v246 offset:5120
	ds_read_b128 v[146:149], v244 offset:1024
	ds_read_b128 v[160:163], v245 offset:1024
	s_waitcnt lgkmcnt(1)
	v_mfma_f32_16x16x32_bf16 v[94:97], v[138:141], v[146:149], v[94:97]
	v_mfma_f32_16x16x32_bf16 v[90:93], v[142:145], v[146:149], v[90:93]
	v_mfma_f32_16x16x32_bf16 v[86:89], v[156:159], v[146:149], v[86:89]
	v_mfma_f32_16x16x32_bf16 v[82:85], v[152:155], v[146:149], v[82:85]
	ds_read_b128 v[146:149], v0 offset:1024
	s_waitcnt lgkmcnt(0)
	v_mfma_f32_16x16x32_bf16 v[110:113], v[138:141], v[146:149], v[110:113]
	v_mfma_f32_16x16x32_bf16 v[106:109], v[142:145], v[146:149], v[106:109]
	v_mfma_f32_16x16x32_bf16 v[102:105], v[156:159], v[146:149], v[102:105]
	v_mfma_f32_16x16x32_bf16 v[98:101], v[152:155], v[146:149], v[98:101]
	ds_read_b128 v[146:149], v243 offset:1024
	s_waitcnt lgkmcnt(0)
	v_mfma_f32_16x16x32_bf16 v[126:129], v[138:141], v[146:149], v[126:129]
	v_mfma_f32_16x16x32_bf16 v[122:125], v[142:145], v[146:149], v[122:125]
	v_mfma_f32_16x16x32_bf16 v[118:121], v[156:159], v[146:149], v[118:121]
	v_mfma_f32_16x16x32_bf16 v[114:117], v[152:155], v[146:149], v[114:117]
	v_mfma_f32_16x16x32_bf16 v[78:81], v[138:141], v[160:163], v[78:81]
	v_mfma_f32_16x16x32_bf16 v[74:77], v[142:145], v[160:163], v[74:77]
	v_mfma_f32_16x16x32_bf16 v[70:73], v[156:159], v[160:163], v[70:73]
	v_mfma_f32_16x16x32_bf16 v[66:69], v[152:155], v[160:163], v[66:69]
	s_cbranch_scc1 .LBB0_879
	s_cmp_eq_u32 s22, 0
	s_cbranch_scc1 .LBB0_877
	v_mov_b32_e32 v0, v196
	v_mov_b64_e32 v[152:153], s[30:31]
	v_and_b32_e32 v247, 15, v0
	v_ashrrev_i32_e32 v248, 7, v0
	v_lshl_or_b32 v148, v248, 6, v247
	v_ashrrev_i32_e32 v149, 31, v148
	v_and_b32_e32 v138, 64, v0
	v_lshrrev_b32_e32 v0, 2, v0
	v_lshl_add_u64 v[170:171], s[42:43], 0, v[148:149]
	v_and_or_b32 v0, v0, 12, v138
	v_mad_u64_u32 v[138:139], s[6:7], v170, s90, v[152:153]
	v_mov_b32_e32 v140, v139
	v_mad_u64_u32 v[140:141], s[6:7], v171, s90, v[140:141]
	v_mov_b32_e32 v139, v140
	s_lshl_b64 s[6:7], s[46:47], 1
	v_lshl_add_u64 v[138:139], v[138:139], 0, s[6:7]
	v_lshlrev_b32_e32 v154, 1, v0
	v_mov_b32_e32 v155, v1
	v_lshl_add_u64 v[138:139], v[138:139], 0, v[154:155]
	v_or_b32_e32 v146, 16, v148
	v_lshl_add_u64 v[140:141], v[138:139], 0, s[94:95]
	v_add_co_u32_e32 v138, vcc, s10, v138
	v_ashrrev_i32_e32 v147, 31, v146
	s_nop 0
	v_addc_co_u32_e32 v139, vcc, 0, v139, vcc
	v_lshl_add_u64 v[188:189], s[42:43], 0, v[146:147]
	global_load_dwordx2 v[166:167], v[138:139], off offset:1024
	global_load_dwordx2 v[142:143], v[140:141], off offset:32
	global_load_dwordx2 v[194:195], v[140:141], off offset:64
	global_load_dwordx2 v[192:193], v[140:141], off offset:96
	v_mad_u64_u32 v[138:139], s[14:15], v188, s90, v[152:153]
	v_mov_b32_e32 v140, v139
	v_mad_u64_u32 v[140:141], s[14:15], v189, s90, v[140:141]
	v_mov_b32_e32 v139, v140
	v_lshl_add_u64 v[138:139], v[138:139], 0, s[6:7]
	v_lshl_add_u64 v[138:139], v[138:139], 0, v[154:155]
	v_or_b32_e32 v144, 32, v148
	v_lshl_add_u64 v[140:141], v[138:139], 0, s[94:95]
	v_add_co_u32_e32 v138, vcc, s10, v138
	v_ashrrev_i32_e32 v145, 31, v144
	s_nop 0
	v_addc_co_u32_e32 v139, vcc, 0, v139, vcc
	v_lshl_add_u64 v[178:179], s[42:43], 0, v[144:145]
	global_load_dwordx2 v[190:191], v[138:139], off offset:1024
	global_load_dwordx2 v[186:187], v[140:141], off offset:32
	global_load_dwordx2 v[184:185], v[140:141], off offset:64
	global_load_dwordx2 v[182:183], v[140:141], off offset:96
	v_mad_u64_u32 v[138:139], s[14:15], v178, s90, v[152:153]
	v_mov_b32_e32 v140, v139
	v_mad_u64_u32 v[140:141], s[14:15], v179, s90, v[140:141]
	v_mov_b32_e32 v139, v140
	v_lshl_add_u64 v[138:139], v[138:139], 0, s[6:7]
	v_lshl_add_u64 v[138:139], v[138:139], 0, v[154:155]
	v_lshl_add_u64 v[140:141], v[138:139], 0, s[94:95]
	v_add_co_u32_e32 v138, vcc, s10, v138
	s_nop 1
	v_addc_co_u32_e32 v139, vcc, 0, v139, vcc
	global_load_dwordx2 v[180:181], v[138:139], off offset:1024
	global_load_dwordx2 v[176:177], v[140:141], off offset:32
	global_load_dwordx2 v[174:175], v[140:141], off offset:64
	global_load_dwordx2 v[168:169], v[140:141], off offset:96
	v_or_b32_e32 v140, 48, v148
	v_ashrrev_i32_e32 v141, 31, v140
	v_lshl_add_u64 v[162:163], s[42:43], 0, v[140:141]
	v_mad_u64_u32 v[138:139], s[14:15], v162, s90, v[152:153]
	v_mov_b32_e32 v156, v139
	v_mad_u64_u32 v[156:157], s[14:15], v163, s90, v[156:157]
	v_mov_b32_e32 v139, v156
	v_lshl_add_u64 v[138:139], v[138:139], 0, s[6:7]
	v_lshl_add_u64 v[138:139], v[138:139], 0, v[154:155]
	v_lshl_add_u64 v[156:157], v[138:139], 0, s[94:95]
	v_add_co_u32_e32 v138, vcc, s10, v138
	s_nop 1
	v_addc_co_u32_e32 v139, vcc, 0, v139, vcc
	global_load_dwordx2 v[164:165], v[138:139], off offset:1024
	global_load_dwordx2 v[160:161], v[156:157], off offset:32
	global_load_dwordx2 v[158:159], v[156:157], off offset:64
	s_nop 0
	global_load_dwordx2 v[156:157], v[156:157], off offset:96
	s_waitcnt vmcnt(0)
	v_lshlrev_b32_e32 v139, 16, v166
	v_mul_f32_e32 v141, 0xbfb8aa3b, v139
	v_exp_f32_e32 v141, v141
	v_pk_add_f32 v[198:199], v[2:3], v[126:127]
	v_pk_add_f32 v[172:173], v[4:5], v[128:129]
	v_or_b32_e32 v138, s46, v0
	v_add_f32_e32 v141, 1.0, v141
	v_rcp_f32_e32 v141, v141
	v_pk_add_f32 v[214:215], v[10:11], v[118:119]
	v_mul_f32_e32 v139, v141, v139
	v_and_b32_e32 v141, 0xffff0000, v166
	v_mul_f32_e32 v145, 0xbfb8aa3b, v141
	v_exp_f32_e32 v145, v145
	v_mul_f32_e32 v139, v139, v198
	v_add_f32_e32 v145, 1.0, v145
	v_rcp_f32_e32 v145, v145
	s_nop 0
	v_mul_f32_e32 v141, v145, v141
	v_mul_f32_e32 v141, v141, v199
	v_cvt_pk_bf16_f32 v198, v139, v141
	v_lshlrev_b32_e32 v139, 16, v167
	v_mul_f32_e32 v141, 0xbfb8aa3b, v139
	v_exp_f32_e32 v141, v141
	s_nop 0
	v_add_f32_e32 v141, 1.0, v141
	v_rcp_f32_e32 v141, v141
	s_nop 0
	v_mul_f32_e32 v139, v141, v139
	v_and_b32_e32 v141, 0xffff0000, v167
	v_mul_f32_e32 v145, 0xbfb8aa3b, v141
	v_exp_f32_e32 v145, v145
	v_mul_f32_e32 v139, v139, v172
	v_mov_b64_e32 v[166:167], s[88:89]
	v_mad_u64_u32 v[212:213], s[14:15], v170, s4, v[166:167]
	v_add_f32_e32 v145, 1.0, v145
	v_rcp_f32_e32 v145, v145
	v_mov_b32_e32 v170, v213
	v_mad_u64_u32 v[170:171], s[14:15], v171, s4, v[170:171]
	v_mul_f32_e32 v141, v145, v141
	v_mul_f32_e32 v141, v141, v173
	v_cvt_pk_bf16_f32 v199, v139, v141
	v_lshlrev_b32_e32 v141, 16, v142
	v_mul_f32_e32 v145, 0xbfb8aa3b, v141
	v_exp_f32_e32 v145, v145
	v_and_b32_e32 v142, 0xffff0000, v142
	v_ashrrev_i32_e32 v139, 31, v138
	v_mov_b32_e32 v213, v170
	v_add_f32_e32 v145, 1.0, v145
	v_rcp_f32_e32 v145, v145
	v_lshlrev_b64 v[170:171], 1, v[138:139]
	v_lshl_add_u64 v[172:173], v[212:213], 0, v[170:171]
	global_store_dwordx2 v[172:173], v[198:199], off
	v_mul_f32_e32 v141, v145, v141
	v_mul_f32_e32 v145, 0xbfb8aa3b, v142
	v_exp_f32_e32 v145, v145
	v_pk_add_f32 v[198:199], v[6:7], v[122:123]
	v_pk_add_f32 v[172:173], v[8:9], v[124:125]
	v_mul_f32_e32 v141, v141, v198
	v_add_f32_e32 v145, 1.0, v145
	v_rcp_f32_e32 v145, v145
	s_nop 0
	v_mul_f32_e32 v142, v145, v142
	v_mul_f32_e32 v142, v142, v199
	v_cvt_pk_bf16_f32 v198, v141, v142
	v_lshlrev_b32_e32 v141, 16, v143
	v_mul_f32_e32 v142, 0xbfb8aa3b, v141
	v_exp_f32_e32 v142, v142
	s_nop 0
	v_add_f32_e32 v142, 1.0, v142
	v_rcp_f32_e32 v142, v142
	s_nop 0
	v_mul_f32_e32 v141, v142, v141
	v_and_b32_e32 v142, 0xffff0000, v143
	v_mul_f32_e32 v143, 0xbfb8aa3b, v142
	v_exp_f32_e32 v143, v143
	v_mul_f32_e32 v141, v141, v172
	v_add_f32_e32 v143, 1.0, v143
	v_rcp_f32_e32 v143, v143
	s_nop 0
	v_mul_f32_e32 v142, v143, v142
	v_mul_f32_e32 v142, v142, v173
	v_cvt_pk_bf16_f32 v199, v141, v142
	v_lshl_add_u64 v[142:143], v[0:1], 0, s[46:47]
	v_lshlrev_b32_e32 v0, 16, v194
	v_mul_f32_e32 v141, 0xbfb8aa3b, v0
	v_exp_f32_e32 v141, v141
	v_lshlrev_b64 v[172:173], 1, v[142:143]
	v_lshl_add_u64 v[212:213], v[212:213], 0, v[172:173]
	global_store_dwordx2 v[212:213], v[198:199], off offset:32
	v_add_f32_e32 v141, 1.0, v141
	v_rcp_f32_e32 v141, v141
	v_pk_add_f32 v[198:199], v[12:13], v[120:121]
	v_mul_f32_e32 v0, v141, v0
	v_and_b32_e32 v141, 0xffff0000, v194
	v_mul_f32_e32 v145, 0xbfb8aa3b, v141
	v_exp_f32_e32 v145, v145
	v_mul_f32_e32 v0, v0, v214
	v_add_f32_e32 v145, 1.0, v145
	v_rcp_f32_e32 v145, v145
	s_nop 0
	v_mul_f32_e32 v141, v145, v141
	v_mul_f32_e32 v141, v141, v215
	v_cvt_pk_bf16_f32 v194, v0, v141
	v_lshlrev_b32_e32 v0, 16, v195
	v_mul_f32_e32 v141, 0xbfb8aa3b, v0
	v_exp_f32_e32 v141, v141
	s_nop 0
	v_add_f32_e32 v141, 1.0, v141
	v_rcp_f32_e32 v141, v141
	s_nop 0
	v_mul_f32_e32 v0, v141, v0
	v_and_b32_e32 v141, 0xffff0000, v195
	v_mul_f32_e32 v145, 0xbfb8aa3b, v141
	v_exp_f32_e32 v145, v145
	v_mul_f32_e32 v0, v0, v198
	v_add_f32_e32 v145, 1.0, v145
	v_rcp_f32_e32 v145, v145
	s_nop 0
	v_mul_f32_e32 v141, v145, v141
	v_mul_f32_e32 v141, v141, v199
	v_cvt_pk_bf16_f32 v195, v0, v141
	v_lshlrev_b32_e32 v0, 16, v192
	v_mul_f32_e32 v141, 0xbfb8aa3b, v0
	v_exp_f32_e32 v141, v141
	v_pk_add_f32 v[198:199], v[14:15], v[114:115]
	global_store_dwordx2 v[212:213], v[194:195], off offset:64
	v_pk_add_f32 v[194:195], v[16:17], v[116:117]
	v_add_f32_e32 v141, 1.0, v141
	v_rcp_f32_e32 v141, v141
	s_nop 0
	v_mul_f32_e32 v0, v141, v0
	v_and_b32_e32 v141, 0xffff0000, v192
	v_mul_f32_e32 v145, 0xbfb8aa3b, v141
	v_exp_f32_e32 v145, v145
	v_mul_f32_e32 v0, v0, v198
	v_add_f32_e32 v145, 1.0, v145
	v_rcp_f32_e32 v145, v145
	s_nop 0
	v_mul_f32_e32 v141, v145, v141
	v_mul_f32_e32 v141, v141, v199
	v_cvt_pk_bf16_f32 v192, v0, v141
	v_lshlrev_b32_e32 v0, 16, v193
	v_mul_f32_e32 v141, 0xbfb8aa3b, v0
	v_exp_f32_e32 v141, v141
	s_nop 0
	v_add_f32_e32 v141, 1.0, v141
	v_rcp_f32_e32 v141, v141
	s_nop 0
	v_mul_f32_e32 v0, v141, v0
	v_and_b32_e32 v141, 0xffff0000, v193
	v_mul_f32_e32 v145, 0xbfb8aa3b, v141
	v_exp_f32_e32 v145, v145
	v_mul_f32_e32 v0, v0, v194
	v_add_f32_e32 v145, 1.0, v145
	v_rcp_f32_e32 v145, v145
	s_nop 0
	v_mul_f32_e32 v141, v145, v141
	v_mul_f32_e32 v141, v141, v195
	v_cvt_pk_bf16_f32 v193, v0, v141
	v_lshlrev_b32_e32 v0, 16, v190
	v_mul_f32_e32 v141, 0xbfb8aa3b, v0
	v_exp_f32_e32 v141, v141
	v_pk_add_f32 v[194:195], v[18:19], v[110:111]
	global_store_dwordx2 v[212:213], v[192:193], off offset:96
	v_pk_add_f32 v[192:193], v[20:21], v[112:113]
	v_add_f32_e32 v141, 1.0, v141
	v_rcp_f32_e32 v141, v141
	s_nop 0
	v_mul_f32_e32 v0, v141, v0
	v_and_b32_e32 v141, 0xffff0000, v190
	v_mul_f32_e32 v145, 0xbfb8aa3b, v141
	v_exp_f32_e32 v145, v145
	v_mul_f32_e32 v0, v0, v194
	v_add_f32_e32 v145, 1.0, v145
	v_rcp_f32_e32 v145, v145
	s_nop 0
	v_mul_f32_e32 v141, v145, v141
	v_mul_f32_e32 v141, v141, v195
	v_cvt_pk_bf16_f32 v190, v0, v141
	v_lshlrev_b32_e32 v0, 16, v191
	v_mul_f32_e32 v141, 0xbfb8aa3b, v0
	v_exp_f32_e32 v141, v141
	s_nop 0
	v_add_f32_e32 v141, 1.0, v141
	v_rcp_f32_e32 v141, v141
	s_nop 0
	v_mul_f32_e32 v0, v141, v0
	v_and_b32_e32 v141, 0xffff0000, v191
	v_mul_f32_e32 v145, 0xbfb8aa3b, v141
	v_exp_f32_e32 v145, v145
	v_mul_f32_e32 v0, v0, v192
	v_add_f32_e32 v145, 1.0, v145
	v_rcp_f32_e32 v145, v145
	s_nop 0
	v_mul_f32_e32 v141, v145, v141
	v_mul_f32_e32 v141, v141, v193
	v_mad_u64_u32 v[192:193], s[14:15], v188, s4, v[166:167]
	v_cvt_pk_bf16_f32 v191, v0, v141
	v_mov_b32_e32 v0, v193
	v_mad_u64_u32 v[188:189], s[14:15], v189, s4, v[0:1]
	v_lshlrev_b32_e32 v0, 16, v186
	v_mul_f32_e32 v141, 0xbfb8aa3b, v0
	v_exp_f32_e32 v141, v141
	v_mov_b32_e32 v193, v188
	v_lshl_add_u64 v[188:189], v[192:193], 0, v[170:171]
	global_store_dwordx2 v[188:189], v[190:191], off
	v_add_f32_e32 v141, 1.0, v141
	v_rcp_f32_e32 v141, v141
	v_pk_add_f32 v[190:191], v[22:23], v[106:107]
	v_pk_add_f32 v[188:189], v[24:25], v[108:109]
	v_mul_f32_e32 v0, v141, v0
	v_and_b32_e32 v141, 0xffff0000, v186
	v_mul_f32_e32 v145, 0xbfb8aa3b, v141
	v_exp_f32_e32 v145, v145
	v_mul_f32_e32 v0, v0, v190
	v_add_f32_e32 v145, 1.0, v145
	v_rcp_f32_e32 v145, v145
	s_nop 0
	v_mul_f32_e32 v141, v145, v141
	v_mul_f32_e32 v141, v141, v191
	v_cvt_pk_bf16_f32 v186, v0, v141
	v_lshlrev_b32_e32 v0, 16, v187
	v_mul_f32_e32 v141, 0xbfb8aa3b, v0
	v_exp_f32_e32 v141, v141
	v_pk_add_f32 v[190:191], v[26:27], v[102:103]
	v_add_f32_e32 v141, 1.0, v141
	v_rcp_f32_e32 v141, v141
	s_nop 0
	v_mul_f32_e32 v0, v141, v0
	v_and_b32_e32 v141, 0xffff0000, v187
	v_mul_f32_e32 v145, 0xbfb8aa3b, v141
	v_exp_f32_e32 v145, v145
	v_mul_f32_e32 v0, v0, v188
	v_add_f32_e32 v145, 1.0, v145
	v_rcp_f32_e32 v145, v145
	s_nop 0
	v_mul_f32_e32 v141, v145, v141
	v_mul_f32_e32 v141, v141, v189
	v_cvt_pk_bf16_f32 v187, v0, v141
	v_lshlrev_b32_e32 v0, 16, v184
	v_mul_f32_e32 v141, 0xbfb8aa3b, v0
	v_exp_f32_e32 v141, v141
	v_lshl_add_u64 v[188:189], v[192:193], 0, v[172:173]
	global_store_dwordx2 v[188:189], v[186:187], off offset:32
	v_pk_add_f32 v[186:187], v[28:29], v[104:105]
	v_add_f32_e32 v141, 1.0, v141
	v_rcp_f32_e32 v141, v141
	s_nop 0
	v_mul_f32_e32 v0, v141, v0
	v_and_b32_e32 v141, 0xffff0000, v184
	v_mul_f32_e32 v145, 0xbfb8aa3b, v141
	v_exp_f32_e32 v145, v145
	v_mul_f32_e32 v0, v0, v190
	v_add_f32_e32 v145, 1.0, v145
	v_rcp_f32_e32 v145, v145
	s_nop 0
	v_mul_f32_e32 v141, v145, v141
	v_mul_f32_e32 v141, v141, v191
	v_cvt_pk_bf16_f32 v184, v0, v141
	v_lshlrev_b32_e32 v0, 16, v185
	v_mul_f32_e32 v141, 0xbfb8aa3b, v0
	v_exp_f32_e32 v141, v141
	s_nop 0
	v_add_f32_e32 v141, 1.0, v141
	v_rcp_f32_e32 v141, v141
	s_nop 0
	v_mul_f32_e32 v0, v141, v0
	v_and_b32_e32 v141, 0xffff0000, v185
	v_mul_f32_e32 v145, 0xbfb8aa3b, v141
	v_exp_f32_e32 v145, v145
	v_mul_f32_e32 v0, v0, v186
	v_add_f32_e32 v145, 1.0, v145
	v_rcp_f32_e32 v145, v145
	s_nop 0
	v_mul_f32_e32 v141, v145, v141
	v_mul_f32_e32 v141, v141, v187
	v_cvt_pk_bf16_f32 v185, v0, v141
	v_lshlrev_b32_e32 v0, 16, v182
	v_mul_f32_e32 v141, 0xbfb8aa3b, v0
	v_exp_f32_e32 v141, v141
	v_pk_add_f32 v[186:187], v[30:31], v[98:99]
	global_store_dwordx2 v[188:189], v[184:185], off offset:64
	v_pk_add_f32 v[184:185], v[32:33], v[100:101]
	v_add_f32_e32 v141, 1.0, v141
	v_rcp_f32_e32 v141, v141
	s_nop 0
	v_mul_f32_e32 v0, v141, v0
	v_and_b32_e32 v141, 0xffff0000, v182
	v_mul_f32_e32 v145, 0xbfb8aa3b, v141
	v_exp_f32_e32 v145, v145
	v_mul_f32_e32 v0, v0, v186
	v_add_f32_e32 v145, 1.0, v145
	v_rcp_f32_e32 v145, v145
	s_nop 0
	v_mul_f32_e32 v141, v145, v141
	v_mul_f32_e32 v141, v141, v187
	v_cvt_pk_bf16_f32 v182, v0, v141
	v_lshlrev_b32_e32 v0, 16, v183
	v_mul_f32_e32 v141, 0xbfb8aa3b, v0
	v_exp_f32_e32 v141, v141
	s_nop 0
	v_add_f32_e32 v141, 1.0, v141
	v_rcp_f32_e32 v141, v141
	s_nop 0
	v_mul_f32_e32 v0, v141, v0
	v_and_b32_e32 v141, 0xffff0000, v183
	v_mul_f32_e32 v145, 0xbfb8aa3b, v141
	v_exp_f32_e32 v145, v145
	v_mul_f32_e32 v0, v0, v184
	v_add_f32_e32 v145, 1.0, v145
	v_rcp_f32_e32 v145, v145
	s_nop 0
	v_mul_f32_e32 v141, v145, v141
	v_mul_f32_e32 v141, v141, v185
	v_cvt_pk_bf16_f32 v183, v0, v141
	v_lshlrev_b32_e32 v0, 16, v180
	v_mul_f32_e32 v141, 0xbfb8aa3b, v0
	v_exp_f32_e32 v141, v141
	v_pk_add_f32 v[184:185], v[34:35], v[94:95]
	global_store_dwordx2 v[188:189], v[182:183], off offset:96
	v_pk_add_f32 v[182:183], v[36:37], v[96:97]
	v_add_f32_e32 v141, 1.0, v141
	v_rcp_f32_e32 v141, v141
	s_nop 0
	v_mul_f32_e32 v0, v141, v0
	v_and_b32_e32 v141, 0xffff0000, v180
	v_mul_f32_e32 v145, 0xbfb8aa3b, v141
	v_exp_f32_e32 v145, v145
	v_mul_f32_e32 v0, v0, v184
	v_add_f32_e32 v145, 1.0, v145
	v_rcp_f32_e32 v145, v145
	s_nop 0
	v_mul_f32_e32 v141, v145, v141
	v_mul_f32_e32 v141, v141, v185
	v_cvt_pk_bf16_f32 v180, v0, v141
	v_lshlrev_b32_e32 v0, 16, v181
	v_mul_f32_e32 v141, 0xbfb8aa3b, v0
	v_exp_f32_e32 v141, v141
	s_nop 0
	v_add_f32_e32 v141, 1.0, v141
	v_rcp_f32_e32 v141, v141
	s_nop 0
	v_mul_f32_e32 v0, v141, v0
	v_and_b32_e32 v141, 0xffff0000, v181
	v_mul_f32_e32 v145, 0xbfb8aa3b, v141
	v_exp_f32_e32 v145, v145
	v_mul_f32_e32 v0, v0, v182
	v_add_f32_e32 v145, 1.0, v145
	v_rcp_f32_e32 v145, v145
	s_nop 0
	v_mul_f32_e32 v141, v145, v141
	v_mul_f32_e32 v141, v141, v183
	v_mad_u64_u32 v[182:183], s[14:15], v178, s4, v[166:167]
	v_cvt_pk_bf16_f32 v181, v0, v141
	v_mov_b32_e32 v0, v183
	v_mad_u64_u32 v[178:179], s[14:15], v179, s4, v[0:1]
	v_lshlrev_b32_e32 v0, 16, v176
	v_mul_f32_e32 v141, 0xbfb8aa3b, v0
	v_exp_f32_e32 v141, v141
	v_mov_b32_e32 v183, v178
	v_lshl_add_u64 v[178:179], v[182:183], 0, v[170:171]
	global_store_dwordx2 v[178:179], v[180:181], off
	v_add_f32_e32 v141, 1.0, v141
	v_rcp_f32_e32 v141, v141
	v_pk_add_f32 v[180:181], v[38:39], v[90:91]
	v_pk_add_f32 v[178:179], v[40:41], v[92:93]
	v_mad_u64_u32 v[166:167], s[14:15], v162, s4, v[166:167]
	v_mul_f32_e32 v0, v141, v0
	v_and_b32_e32 v141, 0xffff0000, v176
	v_mul_f32_e32 v145, 0xbfb8aa3b, v141
	v_exp_f32_e32 v145, v145
	v_mul_f32_e32 v0, v0, v180
	v_add_f32_e32 v145, 1.0, v145
	v_rcp_f32_e32 v145, v145
	s_nop 0
	v_mul_f32_e32 v141, v145, v141
	v_mul_f32_e32 v141, v141, v181
	v_cvt_pk_bf16_f32 v176, v0, v141
	v_lshlrev_b32_e32 v0, 16, v177
	v_mul_f32_e32 v141, 0xbfb8aa3b, v0
	v_exp_f32_e32 v141, v141
	v_pk_add_f32 v[180:181], v[42:43], v[86:87]
	v_add_f32_e32 v141, 1.0, v141
	v_rcp_f32_e32 v141, v141
	s_nop 0
	v_mul_f32_e32 v0, v141, v0
	v_and_b32_e32 v141, 0xffff0000, v177
	v_mul_f32_e32 v145, 0xbfb8aa3b, v141
	v_exp_f32_e32 v145, v145
	v_mul_f32_e32 v0, v0, v178
	v_add_f32_e32 v145, 1.0, v145
	v_rcp_f32_e32 v145, v145
	s_nop 0
	v_mul_f32_e32 v141, v145, v141
	v_mul_f32_e32 v141, v141, v179
	v_cvt_pk_bf16_f32 v177, v0, v141
	v_lshlrev_b32_e32 v0, 16, v174
	v_mul_f32_e32 v141, 0xbfb8aa3b, v0
	v_exp_f32_e32 v141, v141
	v_lshl_add_u64 v[178:179], v[182:183], 0, v[172:173]
	global_store_dwordx2 v[178:179], v[176:177], off offset:32
	v_pk_add_f32 v[176:177], v[44:45], v[88:89]
	v_add_f32_e32 v141, 1.0, v141
	v_rcp_f32_e32 v141, v141
	s_nop 0
	v_mul_f32_e32 v0, v141, v0
	v_and_b32_e32 v141, 0xffff0000, v174
	v_mul_f32_e32 v145, 0xbfb8aa3b, v141
	v_exp_f32_e32 v145, v145
	v_mul_f32_e32 v0, v0, v180
	v_add_f32_e32 v145, 1.0, v145
	v_rcp_f32_e32 v145, v145
	s_nop 0
	v_mul_f32_e32 v141, v145, v141
	v_mul_f32_e32 v141, v141, v181
	v_cvt_pk_bf16_f32 v174, v0, v141
	v_lshlrev_b32_e32 v0, 16, v175
	v_mul_f32_e32 v141, 0xbfb8aa3b, v0
	v_exp_f32_e32 v141, v141
	s_nop 0
	v_add_f32_e32 v141, 1.0, v141
	v_rcp_f32_e32 v141, v141
	s_nop 0
	v_mul_f32_e32 v0, v141, v0
	v_and_b32_e32 v141, 0xffff0000, v175
	v_mul_f32_e32 v145, 0xbfb8aa3b, v141
	v_exp_f32_e32 v145, v145
	v_mul_f32_e32 v0, v0, v176
	v_add_f32_e32 v145, 1.0, v145
	v_rcp_f32_e32 v145, v145
	s_nop 0
	v_mul_f32_e32 v141, v145, v141
	v_mul_f32_e32 v141, v141, v177
	v_cvt_pk_bf16_f32 v175, v0, v141
	v_lshlrev_b32_e32 v0, 16, v168
	v_mul_f32_e32 v141, 0xbfb8aa3b, v0
	v_exp_f32_e32 v141, v141
	v_pk_add_f32 v[176:177], v[46:47], v[82:83]
	global_store_dwordx2 v[178:179], v[174:175], off offset:64
	v_pk_add_f32 v[174:175], v[48:49], v[84:85]
	v_add_f32_e32 v141, 1.0, v141
	v_rcp_f32_e32 v141, v141
	s_nop 0
	v_mul_f32_e32 v0, v141, v0
	v_and_b32_e32 v141, 0xffff0000, v168
	v_mul_f32_e32 v145, 0xbfb8aa3b, v141
	v_exp_f32_e32 v145, v145
	v_mul_f32_e32 v0, v0, v176
	v_add_f32_e32 v145, 1.0, v145
	v_rcp_f32_e32 v145, v145
	s_nop 0
	v_mul_f32_e32 v141, v145, v141
	v_mul_f32_e32 v141, v141, v177
	v_cvt_pk_bf16_f32 v168, v0, v141
	v_lshlrev_b32_e32 v0, 16, v169
	v_mul_f32_e32 v141, 0xbfb8aa3b, v0
	v_exp_f32_e32 v141, v141
	s_nop 0
	v_add_f32_e32 v141, 1.0, v141
	v_rcp_f32_e32 v141, v141
	s_nop 0
	v_mul_f32_e32 v0, v141, v0
	v_and_b32_e32 v141, 0xffff0000, v169
	v_mul_f32_e32 v145, 0xbfb8aa3b, v141
	v_exp_f32_e32 v145, v145
	v_mul_f32_e32 v0, v0, v174
	v_add_f32_e32 v145, 1.0, v145
	v_rcp_f32_e32 v145, v145
	s_nop 0
	v_mul_f32_e32 v141, v145, v141
	v_mul_f32_e32 v141, v141, v175
	v_cvt_pk_bf16_f32 v169, v0, v141
	v_lshlrev_b32_e32 v0, 16, v164
	v_mul_f32_e32 v141, 0xbfb8aa3b, v0
	v_exp_f32_e32 v141, v141
	v_pk_add_f32 v[174:175], v[50:51], v[78:79]
	global_store_dwordx2 v[178:179], v[168:169], off offset:96
	v_pk_add_f32 v[168:169], v[52:53], v[80:81]
	v_add_f32_e32 v141, 1.0, v141
	v_rcp_f32_e32 v141, v141
	s_nop 0
	v_mul_f32_e32 v0, v141, v0
	v_and_b32_e32 v141, 0xffff0000, v164
	v_mul_f32_e32 v145, 0xbfb8aa3b, v141
	v_exp_f32_e32 v145, v145
	v_mul_f32_e32 v0, v0, v174
	v_add_f32_e32 v145, 1.0, v145
	v_rcp_f32_e32 v145, v145
	s_nop 0
	v_mul_f32_e32 v141, v145, v141
	v_mul_f32_e32 v141, v141, v175
	v_cvt_pk_bf16_f32 v164, v0, v141
	v_lshlrev_b32_e32 v0, 16, v165
	v_mul_f32_e32 v141, 0xbfb8aa3b, v0
	v_exp_f32_e32 v141, v141
	s_nop 0
	v_add_f32_e32 v141, 1.0, v141
	v_rcp_f32_e32 v141, v141
	s_nop 0
	v_mul_f32_e32 v0, v141, v0
	v_and_b32_e32 v141, 0xffff0000, v165
	v_mul_f32_e32 v145, 0xbfb8aa3b, v141
	v_exp_f32_e32 v145, v145
	v_mul_f32_e32 v0, v0, v168
	v_add_f32_e32 v145, 1.0, v145
	v_rcp_f32_e32 v145, v145
	s_nop 0
	v_mul_f32_e32 v141, v145, v141
	v_mul_f32_e32 v141, v141, v169
	v_cvt_pk_bf16_f32 v165, v0, v141
	v_mov_b32_e32 v0, v167
	v_mad_u64_u32 v[162:163], s[14:15], v163, s4, v[0:1]
	v_lshlrev_b32_e32 v0, 16, v160
	v_mul_f32_e32 v141, 0xbfb8aa3b, v0
	v_exp_f32_e32 v141, v141
	v_mov_b32_e32 v167, v162
	v_lshl_add_u64 v[162:163], v[166:167], 0, v[170:171]
	global_store_dwordx2 v[162:163], v[164:165], off
	v_add_f32_e32 v141, 1.0, v141
	v_rcp_f32_e32 v141, v141
	v_pk_add_f32 v[164:165], v[54:55], v[74:75]
	v_pk_add_f32 v[162:163], v[56:57], v[76:77]
	v_mul_f32_e32 v0, v141, v0
	v_and_b32_e32 v141, 0xffff0000, v160
	v_mul_f32_e32 v145, 0xbfb8aa3b, v141
	v_exp_f32_e32 v145, v145
	v_mul_f32_e32 v0, v0, v164
	v_add_f32_e32 v145, 1.0, v145
	v_rcp_f32_e32 v145, v145
	s_nop 0
	v_mul_f32_e32 v141, v145, v141
	v_mul_f32_e32 v141, v141, v165
	v_cvt_pk_bf16_f32 v160, v0, v141
	v_lshlrev_b32_e32 v0, 16, v161
	v_mul_f32_e32 v141, 0xbfb8aa3b, v0
	v_exp_f32_e32 v141, v141
	v_pk_add_f32 v[164:165], v[58:59], v[70:71]
	v_add_f32_e32 v141, 1.0, v141
	v_rcp_f32_e32 v141, v141
	s_nop 0
	v_mul_f32_e32 v0, v141, v0
	v_and_b32_e32 v141, 0xffff0000, v161
	v_mul_f32_e32 v145, 0xbfb8aa3b, v141
	v_exp_f32_e32 v145, v145
	v_mul_f32_e32 v0, v0, v162
	v_add_f32_e32 v145, 1.0, v145
	v_rcp_f32_e32 v145, v145
	s_nop 0
	v_mul_f32_e32 v141, v145, v141
	v_mul_f32_e32 v141, v141, v163
	v_cvt_pk_bf16_f32 v161, v0, v141
	v_lshlrev_b32_e32 v0, 16, v158
	v_mul_f32_e32 v141, 0xbfb8aa3b, v0
	v_exp_f32_e32 v141, v141
	v_lshl_add_u64 v[162:163], v[166:167], 0, v[172:173]
	global_store_dwordx2 v[162:163], v[160:161], off offset:32
	v_pk_add_f32 v[160:161], v[60:61], v[72:73]
	v_add_f32_e32 v141, 1.0, v141
	v_rcp_f32_e32 v141, v141
	s_nop 0
	v_mul_f32_e32 v0, v141, v0
	v_and_b32_e32 v141, 0xffff0000, v158
	v_mul_f32_e32 v145, 0xbfb8aa3b, v141
	v_exp_f32_e32 v145, v145
	v_mul_f32_e32 v0, v0, v164
	v_add_f32_e32 v145, 1.0, v145
	v_rcp_f32_e32 v145, v145
	s_nop 0
	v_mul_f32_e32 v141, v145, v141
	v_mul_f32_e32 v141, v141, v165
	v_cvt_pk_bf16_f32 v158, v0, v141
	v_lshlrev_b32_e32 v0, 16, v159
	v_mul_f32_e32 v141, 0xbfb8aa3b, v0
	v_exp_f32_e32 v141, v141
	s_nop 0
	v_add_f32_e32 v141, 1.0, v141
	v_rcp_f32_e32 v141, v141
	s_nop 0
	v_mul_f32_e32 v0, v141, v0
	v_and_b32_e32 v141, 0xffff0000, v159
	v_mul_f32_e32 v145, 0xbfb8aa3b, v141
	v_exp_f32_e32 v145, v145
	v_mul_f32_e32 v0, v0, v160
	v_add_f32_e32 v145, 1.0, v145
	v_rcp_f32_e32 v145, v145
	s_nop 0
	v_mul_f32_e32 v141, v145, v141
	v_mul_f32_e32 v141, v141, v161
	v_cvt_pk_bf16_f32 v159, v0, v141
	v_lshlrev_b32_e32 v0, 16, v156
	v_mul_f32_e32 v141, 0xbfb8aa3b, v0
	v_exp_f32_e32 v141, v141
	v_pk_add_f32 v[160:161], v[62:63], v[66:67]
	global_store_dwordx2 v[162:163], v[158:159], off offset:64
	v_pk_add_f32 v[158:159], v[64:65], v[68:69]
	v_add_f32_e32 v141, 1.0, v141
	v_rcp_f32_e32 v141, v141
	s_nop 0
	v_mul_f32_e32 v0, v141, v0
	v_and_b32_e32 v141, 0xffff0000, v156
	v_mul_f32_e32 v145, 0xbfb8aa3b, v141
	v_exp_f32_e32 v145, v145
	v_mul_f32_e32 v0, v0, v160
	v_add_f32_e32 v145, 1.0, v145
	v_rcp_f32_e32 v145, v145
	s_nop 0
	v_mul_f32_e32 v141, v145, v141
	v_mul_f32_e32 v141, v141, v161
	v_cvt_pk_bf16_f32 v156, v0, v141
	v_lshlrev_b32_e32 v0, 16, v157
	v_mul_f32_e32 v141, 0xbfb8aa3b, v0
	v_exp_f32_e32 v141, v141
	s_nop 0
	v_add_f32_e32 v141, 1.0, v141
	v_rcp_f32_e32 v141, v141
	s_nop 0
	v_mul_f32_e32 v0, v141, v0
	v_and_b32_e32 v141, 0xffff0000, v157
	v_mul_f32_e32 v145, 0xbfb8aa3b, v141
	v_exp_f32_e32 v145, v145
	v_mul_f32_e32 v0, v0, v158
	v_add_f32_e32 v145, 1.0, v145
	v_rcp_f32_e32 v145, v145
	s_nop 0
	v_mul_f32_e32 v141, v145, v141
	v_mul_f32_e32 v141, v141, v159
	v_cvt_pk_bf16_f32 v157, v0, v141
	global_store_dwordx2 v[162:163], v[156:157], off offset:96
	v_mul_lo_u32 v0, v248, s23
	v_or_b32_e32 v141, s11, v247
	v_sub_u32_e32 v0, v0, v141
	v_and_b32_e32 v141, 0xfff, v0
	v_or_b32_e32 v141, s40, v141
	v_mad_u64_u32 v[156:157], s[14:15], v141, s90, v[152:153]
	v_mad_i32_i24 v157, s41, v220, v157
	v_lshl_add_u64 v[156:157], v[156:157], 0, s[6:7]
	v_lshl_add_u64 v[156:157], v[156:157], 0, v[154:155]
	v_add_u32_e32 v141, 0xff0, v0
	v_lshl_add_u64 v[158:159], v[156:157], 0, s[94:95]
	v_add_co_u32_e32 v156, vcc, s10, v156
	v_and_b32_e32 v141, 0xfff, v141
	s_nop 0
	v_addc_co_u32_e32 v157, vcc, 0, v157, vcc
	v_or_b32_e32 v141, s40, v141
	global_load_dwordx2 v[182:183], v[156:157], off offset:1024
	global_load_dwordx2 v[180:181], v[158:159], off offset:32
	global_load_dwordx2 v[178:179], v[158:159], off offset:64
	global_load_dwordx2 v[176:177], v[158:159], off offset:96
	v_mad_u64_u32 v[156:157], s[14:15], v141, s90, v[152:153]
	v_mad_i32_i24 v157, s41, v220, v157
	v_lshl_add_u64 v[156:157], v[156:157], 0, s[6:7]
	v_lshl_add_u64 v[156:157], v[156:157], 0, v[154:155]
	v_add_u32_e32 v141, 0xfe0, v0
	v_lshl_add_u64 v[158:159], v[156:157], 0, s[94:95]
	v_add_co_u32_e32 v156, vcc, s10, v156
	v_and_b32_e32 v141, 0xfff, v141
	s_nop 0
	v_addc_co_u32_e32 v157, vcc, 0, v157, vcc
	v_or_b32_e32 v141, s40, v141
	v_add_u32_e32 v0, 0xfd0, v0
	global_load_dwordx2 v[174:175], v[156:157], off offset:1024
	global_load_dwordx2 v[172:173], v[158:159], off offset:32
	global_load_dwordx2 v[170:171], v[158:159], off offset:64
	global_load_dwordx2 v[168:169], v[158:159], off offset:96
	v_mad_u64_u32 v[156:157], s[14:15], v141, s90, v[152:153]
	v_and_b32_e32 v0, 0xfff, v0
	v_mad_i32_i24 v157, s41, v220, v157
	v_or_b32_e32 v0, s40, v0
	v_lshl_add_u64 v[156:157], v[156:157], 0, s[6:7]
	v_mad_u64_u32 v[152:153], s[14:15], v0, s90, v[152:153]
	v_lshl_add_u64 v[156:157], v[156:157], 0, v[154:155]
	v_mad_i32_i24 v153, s41, v220, v153
	v_lshl_add_u64 v[158:159], v[156:157], 0, s[94:95]
	v_add_co_u32_e32 v156, vcc, s10, v156
	v_lshl_add_u64 v[152:153], v[152:153], 0, s[6:7]
	s_nop 0
	v_addc_co_u32_e32 v157, vcc, 0, v157, vcc
	v_lshl_add_u64 v[152:153], v[152:153], 0, v[154:155]
	v_lshl_add_u64 v[184:185], v[152:153], 0, s[94:95]
	v_add_co_u32_e32 v152, vcc, 0x114ed000, v152
	global_load_dwordx2 v[166:167], v[156:157], off offset:1024
	global_load_dwordx2 v[164:165], v[158:159], off offset:32
	global_load_dwordx2 v[162:163], v[158:159], off offset:64
	global_load_dwordx2 v[160:161], v[158:159], off offset:96
	v_addc_co_u32_e32 v153, vcc, 0, v153, vcc
	global_load_dwordx2 v[158:159], v[152:153], off offset:1024
	global_load_dwordx2 v[156:157], v[184:185], off offset:32
	global_load_dwordx2 v[154:155], v[184:185], off offset:64
	s_nop 0
	global_load_dwordx2 v[152:153], v[184:185], off offset:96
	v_add_u32_e32 v0, s11, v148
	v_cmp_lt_i32_e32 vcc, 0, v0
	s_and_saveexec_b64 s[6:7], vcc
	s_cbranch_execz .LBB0_870
	s_waitcnt vmcnt(15)
	v_lshlrev_b32_e32 v184, 16, v182
	v_sub_u32_e32 v148, 0x1000, v0
	v_mul_f32_e32 v0, 0xbfb8aa3b, v184
	v_exp_f32_e32 v0, v0
	v_and_b32_e32 v185, 0xffff0000, v182
	v_lshlrev_b32_e32 v182, 16, v183
	v_sub_f32_e32 v127, v3, v127
	v_add_f32_e32 v0, 1.0, v0
	v_rcp_f32_e32 v186, v0
	v_mul_f32_e32 v0, 0xbfb8aa3b, v185
	v_exp_f32_e32 v0, v0
	v_sub_f32_e32 v126, v2, v126
	v_and_b32_e32 v183, 0xffff0000, v183
	v_sub_f32_e32 v129, v5, v129
	v_add_f32_e32 v0, 1.0, v0
	v_rcp_f32_e32 v187, v0
	v_mul_f32_e32 v0, 0xbfb8aa3b, v182
	v_exp_f32_e32 v0, v0
	v_sub_f32_e32 v128, v4, v128
	v_pk_mul_f32 v[184:185], v[186:187], v[184:185]
	v_ashrrev_i32_e32 v149, 31, v148
	v_add_f32_e32 v0, 1.0, v0
	v_pk_mul_f32 v[126:127], v[184:185], v[126:127]
	v_rcp_f32_e32 v184, v0
	v_mul_f32_e32 v0, 0xbfb8aa3b, v183
	v_exp_f32_e32 v0, v0
	v_lshl_add_u64 v[148:149], s[40:41], 0, v[148:149]
	v_cvt_pk_bf16_f32 v126, v126, v127
	v_sub_f32_e32 v123, v7, v123
	v_add_f32_e32 v0, 1.0, v0
	v_rcp_f32_e32 v185, v0
	v_sub_f32_e32 v122, v6, v122
	v_sub_f32_e32 v125, v9, v125
	v_sub_f32_e32 v124, v8, v124
	v_pk_mul_f32 v[182:183], v[184:185], v[182:183]
	v_sub_f32_e32 v119, v11, v119
	v_pk_mul_f32 v[128:129], v[182:183], v[128:129]
	v_sub_f32_e32 v118, v10, v118
	v_cvt_pk_bf16_f32 v127, v128, v129
	v_mov_b64_e32 v[128:129], s[88:89]
	v_mad_u64_u32 v[128:129], s[14:15], v148, s4, v[128:129]
	v_mad_i32_i24 v129, v149, s4, v129
	v_lshl_add_u64 v[148:149], v[138:139], 1, v[128:129]
	global_store_dwordx2 v[148:149], v[126:127], off
	s_waitcnt vmcnt(15)
	v_lshlrev_b32_e32 v126, 16, v180
	v_mul_f32_e32 v0, 0xbfb8aa3b, v126
	v_exp_f32_e32 v0, v0
	v_and_b32_e32 v127, 0xffff0000, v180
	v_sub_f32_e32 v121, v13, v121
	v_sub_f32_e32 v120, v12, v120
	v_add_f32_e32 v0, 1.0, v0
	v_rcp_f32_e32 v148, v0
	v_mul_f32_e32 v0, 0xbfb8aa3b, v127
	v_exp_f32_e32 v0, v0
	v_sub_f32_e32 v115, v15, v115
	v_sub_f32_e32 v114, v14, v114
	v_sub_f32_e32 v117, v17, v117
	v_add_f32_e32 v0, 1.0, v0
	v_rcp_f32_e32 v149, v0
	v_sub_f32_e32 v116, v16, v116
	v_pk_mul_f32 v[126:127], v[148:149], v[126:127]
	s_nop 0
	v_pk_mul_f32 v[122:123], v[126:127], v[122:123]
	v_lshlrev_b32_e32 v126, 16, v181
	v_mul_f32_e32 v0, 0xbfb8aa3b, v126
	v_exp_f32_e32 v0, v0
	v_and_b32_e32 v127, 0xffff0000, v181
	v_cvt_pk_bf16_f32 v122, v122, v123
	v_add_f32_e32 v0, 1.0, v0
	v_rcp_f32_e32 v148, v0
	v_mul_f32_e32 v0, 0xbfb8aa3b, v127
	v_exp_f32_e32 v0, v0
	s_nop 0
	v_add_f32_e32 v0, 1.0, v0
	v_rcp_f32_e32 v149, v0
	s_nop 0
	v_pk_mul_f32 v[126:127], v[148:149], v[126:127]
	s_nop 0
	v_pk_mul_f32 v[124:125], v[126:127], v[124:125]
	s_nop 0
	v_cvt_pk_bf16_f32 v123, v124, v125
	v_lshl_add_u64 v[124:125], v[142:143], 1, v[128:129]
	global_store_dwordx2 v[124:125], v[122:123], off offset:32
	s_waitcnt vmcnt(15)
	v_lshlrev_b32_e32 v122, 16, v178
	v_mul_f32_e32 v0, 0xbfb8aa3b, v122
	v_exp_f32_e32 v0, v0
	v_and_b32_e32 v123, 0xffff0000, v178
	v_add_f32_e32 v0, 1.0, v0
	v_rcp_f32_e32 v126, v0
	v_mul_f32_e32 v0, 0xbfb8aa3b, v123
	v_exp_f32_e32 v0, v0
	s_nop 0
	v_add_f32_e32 v0, 1.0, v0
	v_rcp_f32_e32 v127, v0
	s_nop 0
	v_pk_mul_f32 v[122:123], v[126:127], v[122:123]
	s_nop 0
	v_pk_mul_f32 v[118:119], v[122:123], v[118:119]
	v_lshlrev_b32_e32 v122, 16, v179
	v_mul_f32_e32 v0, 0xbfb8aa3b, v122
	v_exp_f32_e32 v0, v0
	v_and_b32_e32 v123, 0xffff0000, v179
	v_cvt_pk_bf16_f32 v118, v118, v119
	v_add_f32_e32 v0, 1.0, v0
	v_rcp_f32_e32 v126, v0
	v_mul_f32_e32 v0, 0xbfb8aa3b, v123
	v_exp_f32_e32 v0, v0
	s_nop 0
	v_add_f32_e32 v0, 1.0, v0
	v_rcp_f32_e32 v127, v0
	s_nop 0
	v_pk_mul_f32 v[122:123], v[126:127], v[122:123]
	s_nop 0
	v_pk_mul_f32 v[120:121], v[122:123], v[120:121]
	s_nop 0
	v_cvt_pk_bf16_f32 v119, v120, v121
	global_store_dwordx2 v[124:125], v[118:119], off offset:64
	s_waitcnt vmcnt(15)
	v_lshlrev_b32_e32 v118, 16, v176
	v_mul_f32_e32 v0, 0xbfb8aa3b, v118
	v_exp_f32_e32 v0, v0
	v_and_b32_e32 v119, 0xffff0000, v176
	v_add_f32_e32 v0, 1.0, v0
	v_rcp_f32_e32 v120, v0
	v_mul_f32_e32 v0, 0xbfb8aa3b, v119
	v_exp_f32_e32 v0, v0
	s_nop 0
	v_add_f32_e32 v0, 1.0, v0
	v_rcp_f32_e32 v121, v0
	s_nop 0
	v_pk_mul_f32 v[118:119], v[120:121], v[118:119]
	s_nop 0
	v_pk_mul_f32 v[114:115], v[118:119], v[114:115]
	v_lshlrev_b32_e32 v118, 16, v177
	v_mul_f32_e32 v0, 0xbfb8aa3b, v118
	v_exp_f32_e32 v0, v0
	v_and_b32_e32 v119, 0xffff0000, v177
	v_cvt_pk_bf16_f32 v114, v114, v115
	v_add_f32_e32 v0, 1.0, v0
	v_rcp_f32_e32 v120, v0
	v_mul_f32_e32 v0, 0xbfb8aa3b, v119
	v_exp_f32_e32 v0, v0
	s_nop 0
	v_add_f32_e32 v0, 1.0, v0
	v_rcp_f32_e32 v121, v0
	s_nop 0
	v_pk_mul_f32 v[118:119], v[120:121], v[118:119]
	s_nop 0
	v_pk_mul_f32 v[116:117], v[118:119], v[116:117]
	s_nop 0
	v_cvt_pk_bf16_f32 v115, v116, v117
	global_store_dwordx2 v[124:125], v[114:115], off offset:96

.LBB0_1082:
	v_add_u32_e32 v0, v191, v227
	v_add_u32_e32 v2, v225, v226
	ds_read_b128 v[140:143], v0 offset:32768
	ds_read_b128 v[152:155], v0 offset:34816
	ds_read_b128 v[144:147], v229
	ds_read_b128 v[156:159], v230
	ds_read_b128 v[160:163], v231
	ds_read_b128 v[164:167], v2
	ds_read_b128 v[168:171], v0 offset:36864
	ds_read_b128 v[172:175], v0 offset:38912
	s_add_i32 s13, s13, 1
	s_cmp_lg_u32 s13, s51
	s_waitcnt lgkmcnt(5)
	v_mfma_f32_16x16x32_bf16 v[128:131], v[140:143], v[144:147], v[128:131]
	v_mfma_f32_16x16x32_bf16 v[124:127], v[152:155], v[144:147], v[124:127]
	s_waitcnt lgkmcnt(4)
	v_mfma_f32_16x16x32_bf16 v[112:115], v[140:143], v[156:159], v[112:115]
	v_mfma_f32_16x16x32_bf16 v[108:111], v[152:155], v[156:159], v[108:111]
	s_waitcnt lgkmcnt(1)
	v_mfma_f32_16x16x32_bf16 v[120:123], v[168:171], v[144:147], v[120:123]
	v_mfma_f32_16x16x32_bf16 v[104:107], v[168:171], v[156:159], v[104:107]
	v_mfma_f32_16x16x32_bf16 v[96:99], v[140:143], v[160:163], v[96:99]
	v_mfma_f32_16x16x32_bf16 v[92:95], v[152:155], v[160:163], v[92:95]
	s_waitcnt lgkmcnt(0)
	v_mfma_f32_16x16x32_bf16 v[116:119], v[172:175], v[144:147], v[116:119]
	v_mfma_f32_16x16x32_bf16 v[100:103], v[172:175], v[156:159], v[100:103]
	v_mfma_f32_16x16x32_bf16 v[88:91], v[168:171], v[160:163], v[88:91]
	v_mfma_f32_16x16x32_bf16 v[84:87], v[172:175], v[160:163], v[84:87]
	v_mfma_f32_16x16x32_bf16 v[80:83], v[140:143], v[164:167], v[80:83]
	v_mfma_f32_16x16x32_bf16 v[76:79], v[152:155], v[164:167], v[76:79]
	v_mfma_f32_16x16x32_bf16 v[72:75], v[168:171], v[164:167], v[72:75]
	v_mfma_f32_16x16x32_bf16 v[68:71], v[172:175], v[164:167], v[68:71]
	ds_read_b128 v[140:143], v0 offset:33792
	ds_read_b128 v[144:147], v0 offset:35840
	ds_read_b128 v[156:159], v0 offset:39936
	ds_read_b128 v[160:163], v0 offset:37888
	ds_read_b128 v[152:155], v229 offset:1024
	ds_read_b128 v[164:167], v230 offset:1024
	s_waitcnt lgkmcnt(1)
	v_mfma_f32_16x16x32_bf16 v[128:131], v[140:143], v[152:155], v[128:131]
	v_mfma_f32_16x16x32_bf16 v[124:127], v[144:147], v[152:155], v[124:127]
	v_mfma_f32_16x16x32_bf16 v[120:123], v[160:163], v[152:155], v[120:123]
	v_mfma_f32_16x16x32_bf16 v[116:119], v[156:159], v[152:155], v[116:119]
	ds_read_b128 v[152:155], v231 offset:1024
	s_waitcnt lgkmcnt(1)
	v_mfma_f32_16x16x32_bf16 v[112:115], v[140:143], v[164:167], v[112:115]
	v_mfma_f32_16x16x32_bf16 v[108:111], v[144:147], v[164:167], v[108:111]
	v_mfma_f32_16x16x32_bf16 v[104:107], v[160:163], v[164:167], v[104:107]
	v_mfma_f32_16x16x32_bf16 v[100:103], v[156:159], v[164:167], v[100:103]
	ds_read_b128 v[164:167], v2 offset:1024
	s_waitcnt lgkmcnt(1)
	v_mfma_f32_16x16x32_bf16 v[96:99], v[140:143], v[152:155], v[96:99]
	v_mfma_f32_16x16x32_bf16 v[92:95], v[144:147], v[152:155], v[92:95]
	v_mfma_f32_16x16x32_bf16 v[88:91], v[160:163], v[152:155], v[88:91]
	v_mfma_f32_16x16x32_bf16 v[84:87], v[156:159], v[152:155], v[84:87]
	s_waitcnt lgkmcnt(0)
	v_mfma_f32_16x16x32_bf16 v[80:83], v[140:143], v[164:167], v[80:83]
	v_mfma_f32_16x16x32_bf16 v[76:79], v[144:147], v[164:167], v[76:79]
	v_mfma_f32_16x16x32_bf16 v[72:75], v[160:163], v[164:167], v[72:75]
	v_mfma_f32_16x16x32_bf16 v[68:71], v[156:159], v[164:167], v[68:71]
	s_cbranch_scc1 .LBB0_1116
	s_ashr_i32 s13, s50, 2
	s_mul_i32 s13, s13, s62
	s_add_i32 s13, s13, s86
	s_mul_hi_i32 s15, s13, 0x2aaaaaab
	s_lshr_b32 s16, s15, 31
	s_ashr_i32 s15, s15, 3
	s_add_i32 s15, s15, s16
	s_mul_i32 s16, s15, 48
	v_mov_b32_e32 v0, v196
	s_sub_i32 s40, s13, s16
	s_movk_i32 s36, 0xffc0
	v_and_b32_e32 v2, 15, v0
	v_ashrrev_i32_e32 v140, 1, v0
	v_and_b32_e32 v3, 64, v0
	s_ashr_i32 s41, s40, 31
	v_and_or_b32 v2, v140, s36, v2
	v_lshrrev_b32_e32 v0, 2, v0
	s_lshl_b64 s[16:17], s[40:41], 8
	v_and_or_b32 v178, v0, 12, v3
	v_ashrrev_i32_e32 v3, 31, v2
	v_lshl_add_u64 v[140:141], s[16:17], 0, v[2:3]
	v_mov_b64_e32 v[142:143], s[30:31]
	s_and_b32 s13, s50, 3
	s_lshl_b32 s46, s15, 7
	v_mad_u64_u32 v[144:145], s[44:45], v140, s90, v[142:143]
	s_ashr_i32 s47, s46, 31
	v_mad_i32_i24 v145, v141, s90, v145
	s_lshl_b32 s36, s13, 12
	v_lshl_add_u64 v[140:141], v[144:145], 0, s[36:37]
	s_lshl_b64 s[44:45], s[46:47], 1
	v_lshl_add_u64 v[140:141], v[140:141], 0, s[44:45]
	v_lshlrev_b32_e32 v0, 1, v178
	s_mov_b32 s47, 0x114f0000
	v_lshl_add_u64 v[140:141], v[140:141], 0, v[0:1]
	s_mov_b64 s[82:83], 0x114f0800
	v_lshl_add_u64 v[144:145], v[140:141], 0, s[82:83]
	v_add_co_u32_e32 v140, vcc, s47, v140
	v_or_b32_e32 v170, 16, v2
	s_nop 0
	v_addc_co_u32_e32 v141, vcc, 0, v141, vcc
	v_ashrrev_i32_e32 v171, 31, v170
	global_load_dwordx2 v[198:199], v[140:141], off offset:2048
	global_load_dwordx2 v[180:181], v[144:145], off offset:32
	global_load_dwordx2 v[176:177], v[144:145], off offset:64
	global_load_dwordx2 v[174:175], v[144:145], off offset:96
	v_lshl_add_u64 v[140:141], s[16:17], 0, v[170:171]
	v_mad_u64_u32 v[144:145], s[48:49], v140, s90, v[142:143]
	v_mad_i32_i24 v145, v141, s90, v145
	v_lshl_add_u64 v[140:141], v[144:145], 0, s[36:37]
	v_lshl_add_u64 v[140:141], v[140:141], 0, s[44:45]
	v_lshl_add_u64 v[140:141], v[140:141], 0, v[0:1]
	v_lshl_add_u64 v[144:145], v[140:141], 0, s[82:83]
	v_add_co_u32_e32 v140, vcc, s47, v140
	v_or_b32_e32 v160, 32, v2
	s_nop 0
	v_addc_co_u32_e32 v141, vcc, 0, v141, vcc
	v_ashrrev_i32_e32 v161, 31, v160
	global_load_dwordx2 v[172:173], v[140:141], off offset:2048
	global_load_dwordx2 v[168:169], v[144:145], off offset:32
	global_load_dwordx2 v[166:167], v[144:145], off offset:64
	global_load_dwordx2 v[164:165], v[144:145], off offset:96
	v_lshl_add_u64 v[140:141], s[16:17], 0, v[160:161]
	v_mad_u64_u32 v[144:145], s[48:49], v140, s90, v[142:143]
	v_mad_i32_i24 v145, v141, s90, v145
	v_lshl_add_u64 v[140:141], v[144:145], 0, s[36:37]
	v_lshl_add_u64 v[140:141], v[140:141], 0, s[44:45]
	v_lshl_add_u64 v[140:141], v[140:141], 0, v[0:1]
	v_lshl_add_u64 v[144:145], v[140:141], 0, s[82:83]
	v_add_co_u32_e32 v140, vcc, s47, v140
	v_or_b32_e32 v148, 48, v2
	s_nop 0
	v_addc_co_u32_e32 v141, vcc, 0, v141, vcc
	v_ashrrev_i32_e32 v149, 31, v148
	global_load_dwordx2 v[162:163], v[140:141], off offset:2048
	global_load_dwordx2 v[158:159], v[144:145], off offset:32
	global_load_dwordx2 v[156:157], v[144:145], off offset:64
	global_load_dwordx2 v[154:155], v[144:145], off offset:96
	v_lshl_add_u64 v[140:141], s[16:17], 0, v[148:149]
	v_mad_u64_u32 v[142:143], s[16:17], v140, s90, v[142:143]
	v_mad_i32_i24 v143, v141, s90, v143
	v_lshl_add_u64 v[140:141], v[142:143], 0, s[36:37]
	v_lshl_add_u64 v[140:141], v[140:141], 0, s[44:45]
	v_lshl_add_u64 v[140:141], v[140:141], 0, v[0:1]
	v_lshl_add_u64 v[142:143], v[140:141], 0, s[82:83]
	v_add_co_u32_e32 v140, vcc, s47, v140
	s_nop 1
	v_addc_co_u32_e32 v141, vcc, 0, v141, vcc
	global_load_dwordx2 v[152:153], v[140:141], off offset:2048
	global_load_dwordx2 v[146:147], v[142:143], off offset:32
	global_load_dwordx2 v[144:145], v[142:143], off offset:64
	s_nop 0
	global_load_dwordx2 v[142:143], v[142:143], off offset:96
	s_waitcnt vmcnt(0)
	v_lshlrev_b32_e32 v0, 16, v198
	v_fma_f32 v28, v128, v0, v28
	v_and_b32_e32 v0, 0xffff0000, v198
	s_cmp_eq_u32 s13, 3
	v_fma_f32 v29, v129, v0, v29
	v_lshlrev_b32_e32 v0, 16, v199
	s_cselect_b64 s[48:49], -1, 0
	s_lshl_b64 s[44:45], s[40:41], 20
	v_or_b32_e32 v140, s46, v178
	v_fma_f32 v30, v130, v0, v30
	v_and_b32_e32 v0, 0xffff0000, v199
	s_cmp_lg_u32 s13, 3
	v_lshlrev_b64 v[178:179], 12, v[2:3]
	v_fmac_f32_e32 v31, v131, v0
	v_ashrrev_i32_e32 v141, 31, v140
	s_cbranch_scc1 .LBB0_1085
	s_add_u32 s16, s12, s44
	s_addc_u32 s17, s20, s45
	v_cvt_pk_bf16_f32 v2, v28, v29
	v_lshl_add_u64 v[28:29], s[16:17], 0, v[178:179]
	v_cvt_pk_bf16_f32 v3, v30, v31
	v_lshl_add_u64 v[28:29], v[140:141], 1, v[28:29]
	global_store_dwordx2 v[28:29], v[2:3], off
	v_mov_b32_e32 v2, v1
	v_mov_b32_e32 v3, v1
	v_mov_b32_e32 v0, v1
	v_mov_b64_e32 v[30:31], v[2:3]
	v_mov_b64_e32 v[28:29], v[0:1]

.LBB0_1128:
	v_add_u32_e32 v0, v228, v224
	ds_read_b128 v[140:143], v235
	ds_read_b128 v[152:155], v235 offset:2048
	ds_read_b128 v[144:147], v232
	ds_read_b128 v[164:167], v0
	ds_read_b128 v[156:159], v233
	ds_read_b128 v[160:163], v234
	ds_read_b128 v[168:171], v235 offset:4096
	ds_read_b128 v[172:175], v235 offset:6144
	s_add_i32 s13, s13, 1
	s_cmp_lg_u32 s13, s51
	s_waitcnt lgkmcnt(5)
	v_mfma_f32_16x16x32_bf16 v[128:131], v[140:143], v[144:147], v[128:131]
	v_mfma_f32_16x16x32_bf16 v[124:127], v[152:155], v[144:147], v[124:127]
	s_waitcnt lgkmcnt(4)
	v_mfma_f32_16x16x32_bf16 v[112:115], v[140:143], v[164:167], v[112:115]
	v_mfma_f32_16x16x32_bf16 v[108:111], v[152:155], v[164:167], v[108:111]
	s_waitcnt lgkmcnt(1)
	v_mfma_f32_16x16x32_bf16 v[120:123], v[168:171], v[144:147], v[120:123]
	v_mfma_f32_16x16x32_bf16 v[104:107], v[168:171], v[164:167], v[104:107]
	v_mfma_f32_16x16x32_bf16 v[96:99], v[140:143], v[156:159], v[96:99]
	v_mfma_f32_16x16x32_bf16 v[92:95], v[152:155], v[156:159], v[92:95]
	s_waitcnt lgkmcnt(0)
	v_mfma_f32_16x16x32_bf16 v[116:119], v[172:175], v[144:147], v[116:119]
	v_mfma_f32_16x16x32_bf16 v[100:103], v[172:175], v[164:167], v[100:103]
	v_mfma_f32_16x16x32_bf16 v[88:91], v[168:171], v[156:159], v[88:91]
	v_mfma_f32_16x16x32_bf16 v[84:87], v[172:175], v[156:159], v[84:87]
	v_mfma_f32_16x16x32_bf16 v[80:83], v[140:143], v[160:163], v[80:83]
	v_mfma_f32_16x16x32_bf16 v[76:79], v[152:155], v[160:163], v[76:79]
	v_mfma_f32_16x16x32_bf16 v[72:75], v[168:171], v[160:163], v[72:75]
	v_mfma_f32_16x16x32_bf16 v[68:71], v[172:175], v[160:163], v[68:71]
	ds_read_b128 v[140:143], v235 offset:1024
	ds_read_b128 v[144:147], v235 offset:3072
	ds_read_b128 v[156:159], v235 offset:7168
	ds_read_b128 v[160:163], v235 offset:5120
	ds_read_b128 v[152:155], v233 offset:1024
	ds_read_b128 v[164:167], v234 offset:1024
	s_waitcnt lgkmcnt(1)
	v_mfma_f32_16x16x32_bf16 v[96:99], v[140:143], v[152:155], v[96:99]
	v_mfma_f32_16x16x32_bf16 v[92:95], v[144:147], v[152:155], v[92:95]
	v_mfma_f32_16x16x32_bf16 v[88:91], v[160:163], v[152:155], v[88:91]
	v_mfma_f32_16x16x32_bf16 v[84:87], v[156:159], v[152:155], v[84:87]
	ds_read_b128 v[152:155], v0 offset:1024
	s_waitcnt lgkmcnt(0)
	v_mfma_f32_16x16x32_bf16 v[112:115], v[140:143], v[152:155], v[112:115]
	v_mfma_f32_16x16x32_bf16 v[108:111], v[144:147], v[152:155], v[108:111]
	v_mfma_f32_16x16x32_bf16 v[104:107], v[160:163], v[152:155], v[104:107]
	v_mfma_f32_16x16x32_bf16 v[100:103], v[156:159], v[152:155], v[100:103]
	ds_read_b128 v[152:155], v232 offset:1024
	s_waitcnt lgkmcnt(0)
	v_mfma_f32_16x16x32_bf16 v[128:131], v[140:143], v[152:155], v[128:131]
	v_mfma_f32_16x16x32_bf16 v[124:127], v[144:147], v[152:155], v[124:127]
	v_mfma_f32_16x16x32_bf16 v[120:123], v[160:163], v[152:155], v[120:123]
	v_mfma_f32_16x16x32_bf16 v[116:119], v[156:159], v[152:155], v[116:119]
	v_mfma_f32_16x16x32_bf16 v[80:83], v[140:143], v[164:167], v[80:83]
	v_mfma_f32_16x16x32_bf16 v[76:79], v[144:147], v[164:167], v[76:79]
	v_mfma_f32_16x16x32_bf16 v[72:75], v[160:163], v[164:167], v[72:75]
	v_mfma_f32_16x16x32_bf16 v[68:71], v[156:159], v[164:167], v[68:71]
	s_cbranch_scc1 .LBB0_1162
	s_ashr_i32 s6, s50, 2
	s_mul_i32 s6, s6, s62
	s_add_i32 s6, s6, s86
	s_mul_hi_i32 s7, s6, 0x2aaaaaab
	s_lshr_b32 s13, s7, 31
	s_ashr_i32 s7, s7, 3
	s_add_i32 s13, s7, s13
	s_mul_i32 s7, s13, 48
	v_mov_b32_e32 v0, v196
	s_sub_i32 s6, s6, s7
	s_movk_i32 s16, 0xffc0
	v_and_b32_e32 v2, 15, v0
	v_ashrrev_i32_e32 v140, 1, v0
	v_and_b32_e32 v3, 64, v0
	s_ashr_i32 s7, s6, 31
	v_and_or_b32 v2, v140, s16, v2
	v_lshrrev_b32_e32 v0, 2, v0
	s_lshl_b64 s[14:15], s[6:7], 8
	v_and_or_b32 v178, v0, 12, v3
	v_ashrrev_i32_e32 v3, 31, v2
	v_lshl_add_u64 v[140:141], s[14:15], 0, v[2:3]
	v_mov_b64_e32 v[142:143], s[30:31]
	s_and_b32 s46, s50, 3
	s_lshl_b32 s40, s13, 7
	v_mad_u64_u32 v[144:145], s[16:17], v140, s90, v[142:143]
	s_ashr_i32 s41, s40, 31
	v_mad_i32_i24 v145, v141, s90, v145
	s_lshl_b32 s36, s46, 12
	v_lshl_add_u64 v[140:141], v[144:145], 0, s[36:37]
	s_lshl_b64 s[16:17], s[40:41], 1
	v_lshl_add_u64 v[140:141], v[140:141], 0, s[16:17]
	v_lshlrev_b32_e32 v0, 1, v178
	v_lshl_add_u64 v[140:141], v[140:141], 0, v[0:1]
	s_mov_b64 s[82:83], 0x114f0800
	v_lshl_add_u64 v[144:145], v[140:141], 0, s[82:83]
	v_add_co_u32_e32 v140, vcc, s47, v140
	v_or_b32_e32 v170, 16, v2
	s_nop 0
	v_addc_co_u32_e32 v141, vcc, 0, v141, vcc
	v_ashrrev_i32_e32 v171, 31, v170
	global_load_dwordx2 v[198:199], v[140:141], off offset:2048
	global_load_dwordx2 v[180:181], v[144:145], off offset:32
	global_load_dwordx2 v[176:177], v[144:145], off offset:64
	global_load_dwordx2 v[174:175], v[144:145], off offset:96
	v_lshl_add_u64 v[140:141], s[14:15], 0, v[170:171]
	v_mad_u64_u32 v[144:145], s[44:45], v140, s90, v[142:143]
	v_mad_i32_i24 v145, v141, s90, v145
	v_lshl_add_u64 v[140:141], v[144:145], 0, s[36:37]
	v_lshl_add_u64 v[140:141], v[140:141], 0, s[16:17]
	v_lshl_add_u64 v[140:141], v[140:141], 0, v[0:1]
	v_lshl_add_u64 v[144:145], v[140:141], 0, s[82:83]
	v_add_co_u32_e32 v140, vcc, s47, v140
	v_or_b32_e32 v160, 32, v2
	s_nop 0
	v_addc_co_u32_e32 v141, vcc, 0, v141, vcc
	v_ashrrev_i32_e32 v161, 31, v160
	global_load_dwordx2 v[172:173], v[140:141], off offset:2048
	global_load_dwordx2 v[168:169], v[144:145], off offset:32
	global_load_dwordx2 v[166:167], v[144:145], off offset:64
	global_load_dwordx2 v[164:165], v[144:145], off offset:96
	v_lshl_add_u64 v[140:141], s[14:15], 0, v[160:161]
	v_mad_u64_u32 v[144:145], s[44:45], v140, s90, v[142:143]
	v_mad_i32_i24 v145, v141, s90, v145
	v_lshl_add_u64 v[140:141], v[144:145], 0, s[36:37]
	v_lshl_add_u64 v[140:141], v[140:141], 0, s[16:17]
	v_lshl_add_u64 v[140:141], v[140:141], 0, v[0:1]
	v_lshl_add_u64 v[144:145], v[140:141], 0, s[82:83]
	v_add_co_u32_e32 v140, vcc, s47, v140
	v_or_b32_e32 v148, 48, v2
	s_nop 0
	v_addc_co_u32_e32 v141, vcc, 0, v141, vcc
	v_ashrrev_i32_e32 v149, 31, v148
	global_load_dwordx2 v[162:163], v[140:141], off offset:2048
	global_load_dwordx2 v[158:159], v[144:145], off offset:32
	global_load_dwordx2 v[156:157], v[144:145], off offset:64
	global_load_dwordx2 v[154:155], v[144:145], off offset:96
	v_lshl_add_u64 v[140:141], s[14:15], 0, v[148:149]
	v_mad_u64_u32 v[142:143], s[14:15], v140, s90, v[142:143]
	v_mad_i32_i24 v143, v141, s90, v143
	v_lshl_add_u64 v[140:141], v[142:143], 0, s[36:37]
	v_lshl_add_u64 v[140:141], v[140:141], 0, s[16:17]
	v_lshl_add_u64 v[140:141], v[140:141], 0, v[0:1]
	v_lshl_add_u64 v[142:143], v[140:141], 0, s[82:83]
	v_add_co_u32_e32 v140, vcc, s47, v140
	s_nop 1
	v_addc_co_u32_e32 v141, vcc, 0, v141, vcc
	global_load_dwordx2 v[152:153], v[140:141], off offset:2048
	global_load_dwordx2 v[146:147], v[142:143], off offset:32
	global_load_dwordx2 v[144:145], v[142:143], off offset:64
	s_nop 0
	global_load_dwordx2 v[142:143], v[142:143], off offset:96
	s_waitcnt vmcnt(0)
	v_lshlrev_b32_e32 v0, 16, v198
	v_fma_f32 v28, v128, v0, v28
	v_and_b32_e32 v0, 0xffff0000, v198
	s_cmp_eq_u32 s46, 3
	v_fma_f32 v29, v129, v0, v29
	v_lshlrev_b32_e32 v0, 16, v199
	s_cselect_b64 s[44:45], -1, 0
	s_lshl_b64 s[6:7], s[6:7], 20
	v_or_b32_e32 v140, s40, v178
	v_fma_f32 v30, v130, v0, v30
	v_and_b32_e32 v0, 0xffff0000, v199
	s_cmp_lg_u32 s46, 3
	v_lshlrev_b64 v[178:179], 12, v[2:3]
	v_fmac_f32_e32 v31, v131, v0
	v_ashrrev_i32_e32 v141, 31, v140
	s_cbranch_scc1 .LBB0_1131
	s_add_u32 s14, s12, s6
	s_addc_u32 s15, s20, s7
	v_cvt_pk_bf16_f32 v2, v28, v29
	v_lshl_add_u64 v[28:29], s[14:15], 0, v[178:179]
	v_cvt_pk_bf16_f32 v3, v30, v31
	v_lshl_add_u64 v[28:29], v[140:141], 1, v[28:29]
	global_store_dwordx2 v[28:29], v[2:3], off
	v_mov_b32_e32 v2, v1
	v_mov_b32_e32 v3, v1
	v_mov_b32_e32 v0, v1
	v_mov_b64_e32 v[30:31], v[2:3]
	v_mov_b64_e32 v[28:29], v[0:1]

.LBB0_1226:
	v_add_u32_e32 v97, v78, v88
	v_add_u32_e32 v130, v86, v87
	ds_read_b128 v[98:101], v97 offset:32768
	ds_read_b128 v[106:109], v97 offset:34816
	ds_read_b128 v[102:105], v90
	ds_read_b128 v[110:113], v91
	ds_read_b128 v[114:117], v92
	ds_read_b128 v[118:121], v130
	ds_read_b128 v[122:125], v97 offset:36864
	ds_read_b128 v[126:129], v97 offset:38912
	s_add_i32 s21, s21, 1
	s_cmp_lg_u32 s21, 32
	s_waitcnt lgkmcnt(5)
	v_mfma_f32_16x16x32_bf16 v[62:65], v[98:101], v[102:105], v[62:65]
	v_mfma_f32_16x16x32_bf16 v[58:61], v[106:109], v[102:105], v[58:61]
	s_waitcnt lgkmcnt(4)
	v_mfma_f32_16x16x32_bf16 v[46:49], v[98:101], v[110:113], v[46:49]
	v_mfma_f32_16x16x32_bf16 v[42:45], v[106:109], v[110:113], v[42:45]
	ds_read_b128 v[132:135], v97 offset:33792
	ds_read_b128 v[136:139], v97 offset:35840
	ds_read_b128 v[140:143], v97 offset:39936
	ds_read_b128 v[144:147], v97 offset:37888
	ds_read_b128 v[152:155], v90 offset:1024
	ds_read_b128 v[156:159], v91 offset:1024
	ds_read_b128 v[160:163], v92 offset:1024
	ds_read_b128 v[164:167], v130 offset:1024
	s_waitcnt lgkmcnt(9)
	v_mfma_f32_16x16x32_bf16 v[54:57], v[122:125], v[102:105], v[54:57]
	v_mfma_f32_16x16x32_bf16 v[38:41], v[122:125], v[110:113], v[38:41]
	v_mfma_f32_16x16x32_bf16 v[30:33], v[98:101], v[114:117], v[30:33]
	v_mfma_f32_16x16x32_bf16 v[26:29], v[106:109], v[114:117], v[26:29]
	s_waitcnt lgkmcnt(8)
	v_mfma_f32_16x16x32_bf16 v[50:53], v[126:129], v[102:105], v[50:53]
	v_mfma_f32_16x16x32_bf16 v[34:37], v[126:129], v[110:113], v[34:37]
	v_mfma_f32_16x16x32_bf16 v[22:25], v[122:125], v[114:117], v[22:25]
	v_mfma_f32_16x16x32_bf16 v[18:21], v[126:129], v[114:117], v[18:21]
	v_mfma_f32_16x16x32_bf16 v[14:17], v[98:101], v[118:121], v[14:17]
	v_mfma_f32_16x16x32_bf16 v[10:13], v[106:109], v[118:121], v[10:13]
	v_mfma_f32_16x16x32_bf16 v[6:9], v[122:125], v[118:121], v[6:9]
	v_mfma_f32_16x16x32_bf16 v[2:5], v[126:129], v[118:121], v[2:5]
	s_waitcnt lgkmcnt(3)
	v_mfma_f32_16x16x32_bf16 v[62:65], v[132:135], v[152:155], v[62:65]
	v_mfma_f32_16x16x32_bf16 v[58:61], v[136:139], v[152:155], v[58:61]
	v_mfma_f32_16x16x32_bf16 v[54:57], v[144:147], v[152:155], v[54:57]
	v_mfma_f32_16x16x32_bf16 v[50:53], v[140:143], v[152:155], v[50:53]
	s_waitcnt lgkmcnt(2)
	v_mfma_f32_16x16x32_bf16 v[46:49], v[132:135], v[156:159], v[46:49]
	v_mfma_f32_16x16x32_bf16 v[42:45], v[136:139], v[156:159], v[42:45]
	v_mfma_f32_16x16x32_bf16 v[38:41], v[144:147], v[156:159], v[38:41]
	v_mfma_f32_16x16x32_bf16 v[34:37], v[140:143], v[156:159], v[34:37]
	s_waitcnt lgkmcnt(1)
	v_mfma_f32_16x16x32_bf16 v[30:33], v[132:135], v[160:163], v[30:33]
	v_mfma_f32_16x16x32_bf16 v[26:29], v[136:139], v[160:163], v[26:29]
	v_mfma_f32_16x16x32_bf16 v[22:25], v[144:147], v[160:163], v[22:25]
	v_mfma_f32_16x16x32_bf16 v[18:21], v[140:143], v[160:163], v[18:21]
	s_waitcnt lgkmcnt(0)
	v_mfma_f32_16x16x32_bf16 v[14:17], v[132:135], v[164:167], v[14:17]
	v_mfma_f32_16x16x32_bf16 v[10:13], v[136:139], v[164:167], v[10:13]
	v_mfma_f32_16x16x32_bf16 v[6:9], v[144:147], v[164:167], v[6:9]
	v_mfma_f32_16x16x32_bf16 v[2:5], v[140:143], v[164:167], v[2:5]
	s_cbranch_scc1 .LBB0_1228
	s_mul_i32 s21, s15, s62
	s_add_i32 s21, s21, s86
	s_mul_hi_i32 s26, s21, 0x2aaaaaab
	s_lshr_b32 s27, s26, 31
	s_ashr_i32 s26, s26, 3
	s_add_i32 s40, s26, s27
	s_mul_i32 s26, s40, 48
	v_mov_b32_e32 v97, v196
	s_sub_i32 s26, s21, s26
	s_ashr_i32 s27, s26, 31
	v_and_b32_e32 v98, 15, v97
	v_and_b32_e32 v99, 64, v97
	v_ashrrev_i32_e32 v100, 1, v97
	v_lshrrev_b32_e32 v97, 2, v97
	v_and_or_b32 v98, v100, s52, v98
	s_lshl_b32 s21, s40, 7
	v_and_b32_e32 v97, 12, v97
	s_lshl_b64 s[26:27], s[26:27], 20
	v_or3_b32 v100, v99, v97, s21
	v_ashrrev_i32_e32 v99, 31, v98
	s_add_u32 s26, s96, s26
	v_lshlrev_b64 v[102:103], 12, v[98:99]
	s_addc_u32 s27, s97, s27
	v_ashrrev_i32_e32 v101, 31, v100
	v_cvt_pk_bf16_f32 v62, v62, v63
	v_cvt_pk_bf16_f32 v63, v64, v65
	v_lshl_add_u64 v[64:65], s[26:27], 0, v[102:103]
	v_lshlrev_b64 v[100:101], 1, v[100:101]
	v_lshl_add_u64 v[64:65], v[64:65], 0, v[100:101]
	v_cvt_pk_bf16_f32 v50, v50, v51
	v_cvt_pk_bf16_f32 v51, v52, v53
	global_store_dwordx2 v[64:65], v[50:51], off offset:96
	v_or_b32_e32 v50, 16, v98
	v_ashrrev_i32_e32 v51, 31, v50
	v_lshlrev_b64 v[50:51], 12, v[50:51]
	v_cvt_pk_bf16_f32 v46, v46, v47
	v_cvt_pk_bf16_f32 v47, v48, v49
	v_lshl_add_u64 v[48:49], s[26:27], 0, v[50:51]
	v_lshl_add_u64 v[48:49], v[48:49], 0, v[100:101]
	v_cvt_pk_bf16_f32 v34, v34, v35
	v_cvt_pk_bf16_f32 v35, v36, v37
	global_store_dwordx2 v[48:49], v[34:35], off offset:96
	v_or_b32_e32 v34, 32, v98
	v_ashrrev_i32_e32 v35, 31, v34
	v_lshlrev_b64 v[34:35], 12, v[34:35]
	v_cvt_pk_bf16_f32 v30, v30, v31
	v_cvt_pk_bf16_f32 v31, v32, v33
	v_lshl_add_u64 v[32:33], s[26:27], 0, v[34:35]
	v_lshl_add_u64 v[32:33], v[32:33], 0, v[100:101]
	v_cvt_pk_bf16_f32 v18, v18, v19
	v_cvt_pk_bf16_f32 v19, v20, v21
	global_store_dwordx2 v[32:33], v[18:19], off offset:96
	v_or_b32_e32 v18, 48, v98
	v_ashrrev_i32_e32 v19, 31, v18
	v_lshlrev_b64 v[18:19], 12, v[18:19]
	v_cvt_pk_bf16_f32 v14, v14, v15
	v_cvt_pk_bf16_f32 v15, v16, v17
	v_lshl_add_u64 v[16:17], s[26:27], 0, v[18:19]
	v_lshl_add_u64 v[16:17], v[16:17], 0, v[100:101]
	v_cvt_pk_bf16_f32 v2, v2, v3
	v_cvt_pk_bf16_f32 v3, v4, v5
	v_cvt_pk_bf16_f32 v58, v58, v59
	v_cvt_pk_bf16_f32 v59, v60, v61
	v_cvt_pk_bf16_f32 v54, v54, v55
	v_cvt_pk_bf16_f32 v55, v56, v57
	v_cvt_pk_bf16_f32 v42, v42, v43
	v_cvt_pk_bf16_f32 v43, v44, v45
	v_cvt_pk_bf16_f32 v38, v38, v39
	v_cvt_pk_bf16_f32 v39, v40, v41
	v_cvt_pk_bf16_f32 v26, v26, v27
	v_cvt_pk_bf16_f32 v27, v28, v29
	v_cvt_pk_bf16_f32 v22, v22, v23
	v_cvt_pk_bf16_f32 v23, v24, v25
	v_cvt_pk_bf16_f32 v10, v10, v11
	v_cvt_pk_bf16_f32 v11, v12, v13
	v_cvt_pk_bf16_f32 v6, v6, v7
	v_cvt_pk_bf16_f32 v7, v8, v9
	global_store_dwordx2 v[16:17], v[2:3], off offset:96
	v_mov_b32_e32 v2, 0
	global_store_dwordx2 v[64:65], v[62:63], off
	global_store_dwordx2 v[64:65], v[58:59], off offset:32
	global_store_dwordx2 v[64:65], v[54:55], off offset:64
	global_store_dwordx2 v[48:49], v[46:47], off
	global_store_dwordx2 v[48:49], v[42:43], off offset:32
	global_store_dwordx2 v[48:49], v[38:39], off offset:64
	global_store_dwordx2 v[32:33], v[30:31], off
	global_store_dwordx2 v[32:33], v[26:27], off offset:32
	global_store_dwordx2 v[32:33], v[22:23], off offset:64
	global_store_dwordx2 v[16:17], v[14:15], off
	global_store_dwordx2 v[16:17], v[10:11], off offset:32
	global_store_dwordx2 v[16:17], v[6:7], off offset:64
	s_add_i32 s15, s15, 1
	s_mov_b32 s21, 0
	v_mov_b32_e32 v3, v2
	v_mov_b32_e32 v4, v2
	v_mov_b32_e32 v5, v2
	v_mov_b32_e32 v6, v2
	v_mov_b32_e32 v7, v2
	v_mov_b32_e32 v8, v2
	v_mov_b32_e32 v9, v2
	v_mov_b32_e32 v10, v2
	v_mov_b32_e32 v11, v2
	v_mov_b32_e32 v12, v2
	v_mov_b32_e32 v13, v2
	v_mov_b32_e32 v14, v2
	v_mov_b32_e32 v15, v2
	v_mov_b32_e32 v16, v2
	v_mov_b32_e32 v17, v2
	v_mov_b32_e32 v18, v2
	v_mov_b32_e32 v19, v2
	v_mov_b32_e32 v20, v2
	v_mov_b32_e32 v21, v2
	v_mov_b32_e32 v22, v2
	v_mov_b32_e32 v23, v2
	v_mov_b32_e32 v24, v2
	v_mov_b32_e32 v25, v2
	v_mov_b32_e32 v26, v2
	v_mov_b32_e32 v27, v2
	v_mov_b32_e32 v28, v2
	v_mov_b32_e32 v29, v2
	v_mov_b32_e32 v30, v2
	v_mov_b32_e32 v31, v2
	v_mov_b32_e32 v32, v2
	v_mov_b32_e32 v33, v2
	v_mov_b32_e32 v34, v2
	v_mov_b32_e32 v35, v2
	v_mov_b32_e32 v36, v2
	v_mov_b32_e32 v37, v2
	v_mov_b32_e32 v38, v2
	v_mov_b32_e32 v39, v2
	v_mov_b32_e32 v40, v2
	v_mov_b32_e32 v41, v2
	v_mov_b32_e32 v42, v2
	v_mov_b32_e32 v43, v2
	v_mov_b32_e32 v44, v2
	v_mov_b32_e32 v45, v2
	v_mov_b32_e32 v46, v2
	v_mov_b32_e32 v47, v2
	v_mov_b32_e32 v48, v2
	v_mov_b32_e32 v49, v2
	v_mov_b32_e32 v50, v2
	v_mov_b32_e32 v51, v2
	v_mov_b32_e32 v52, v2
	v_mov_b32_e32 v53, v2
	v_mov_b32_e32 v54, v2
	v_mov_b32_e32 v55, v2
	v_mov_b32_e32 v56, v2
	v_mov_b32_e32 v57, v2
	v_mov_b32_e32 v58, v2
	v_mov_b32_e32 v59, v2
	v_mov_b32_e32 v60, v2
	v_mov_b32_e32 v61, v2
	v_mov_b32_e32 v62, v2
	v_mov_b32_e32 v63, v2
	v_mov_b32_e32 v64, v2
	v_mov_b32_e32 v65, v2

.LBB0_1234:
	v_add_u32_e32 v97, v89, v85
	ds_read_b128 v[98:101], v96
	ds_read_b128 v[106:109], v96 offset:2048
	ds_read_b128 v[102:105], v93
	ds_read_b128 v[118:121], v97
	ds_read_b128 v[110:113], v94
	ds_read_b128 v[114:117], v95
	ds_read_b128 v[122:125], v96 offset:4096
	ds_read_b128 v[126:129], v96 offset:6144
	s_add_i32 s21, s21, 1
	s_cmp_lg_u32 s21, 32
	s_waitcnt lgkmcnt(5)
	v_mfma_f32_16x16x32_bf16 v[62:65], v[98:101], v[102:105], v[62:65]
	v_mfma_f32_16x16x32_bf16 v[58:61], v[106:109], v[102:105], v[58:61]
	s_waitcnt lgkmcnt(4)
	v_mfma_f32_16x16x32_bf16 v[46:49], v[98:101], v[118:121], v[46:49]
	v_mfma_f32_16x16x32_bf16 v[42:45], v[106:109], v[118:121], v[42:45]
	ds_read_b128 v[132:135], v96 offset:1024
	ds_read_b128 v[136:139], v96 offset:3072
	ds_read_b128 v[140:143], v96 offset:7168
	ds_read_b128 v[144:147], v96 offset:5120
	ds_read_b128 v[152:155], v94 offset:1024
	ds_read_b128 v[156:159], v95 offset:1024
	ds_read_b128 v[160:163], v97 offset:1024
	ds_read_b128 v[164:167], v93 offset:1024
	s_waitcnt lgkmcnt(9)
	v_mfma_f32_16x16x32_bf16 v[54:57], v[122:125], v[102:105], v[54:57]
	v_mfma_f32_16x16x32_bf16 v[38:41], v[122:125], v[118:121], v[38:41]
	v_mfma_f32_16x16x32_bf16 v[30:33], v[98:101], v[110:113], v[30:33]
	v_mfma_f32_16x16x32_bf16 v[26:29], v[106:109], v[110:113], v[26:29]
	s_waitcnt lgkmcnt(8)
	v_mfma_f32_16x16x32_bf16 v[50:53], v[126:129], v[102:105], v[50:53]
	v_mfma_f32_16x16x32_bf16 v[34:37], v[126:129], v[118:121], v[34:37]
	v_mfma_f32_16x16x32_bf16 v[22:25], v[122:125], v[110:113], v[22:25]
	v_mfma_f32_16x16x32_bf16 v[18:21], v[126:129], v[110:113], v[18:21]
	v_mfma_f32_16x16x32_bf16 v[14:17], v[98:101], v[114:117], v[14:17]
	v_mfma_f32_16x16x32_bf16 v[10:13], v[106:109], v[114:117], v[10:13]
	v_mfma_f32_16x16x32_bf16 v[6:9], v[122:125], v[114:117], v[6:9]
	v_mfma_f32_16x16x32_bf16 v[2:5], v[126:129], v[114:117], v[2:5]
	s_waitcnt lgkmcnt(3)
	v_mfma_f32_16x16x32_bf16 v[30:33], v[132:135], v[152:155], v[30:33]
	v_mfma_f32_16x16x32_bf16 v[26:29], v[136:139], v[152:155], v[26:29]
	v_mfma_f32_16x16x32_bf16 v[22:25], v[144:147], v[152:155], v[22:25]
	v_mfma_f32_16x16x32_bf16 v[18:21], v[140:143], v[152:155], v[18:21]
	s_waitcnt lgkmcnt(1)
	v_mfma_f32_16x16x32_bf16 v[46:49], v[132:135], v[160:163], v[46:49]
	v_mfma_f32_16x16x32_bf16 v[42:45], v[136:139], v[160:163], v[42:45]
	v_mfma_f32_16x16x32_bf16 v[38:41], v[144:147], v[160:163], v[38:41]
	v_mfma_f32_16x16x32_bf16 v[34:37], v[140:143], v[160:163], v[34:37]
	s_waitcnt lgkmcnt(0)
	v_mfma_f32_16x16x32_bf16 v[62:65], v[132:135], v[164:167], v[62:65]
	v_mfma_f32_16x16x32_bf16 v[58:61], v[136:139], v[164:167], v[58:61]
	v_mfma_f32_16x16x32_bf16 v[54:57], v[144:147], v[164:167], v[54:57]
	v_mfma_f32_16x16x32_bf16 v[50:53], v[140:143], v[164:167], v[50:53]
	v_mfma_f32_16x16x32_bf16 v[14:17], v[132:135], v[156:159], v[14:17]
	v_mfma_f32_16x16x32_bf16 v[10:13], v[136:139], v[156:159], v[10:13]
	v_mfma_f32_16x16x32_bf16 v[6:9], v[144:147], v[156:159], v[6:9]
	v_mfma_f32_16x16x32_bf16 v[2:5], v[140:143], v[156:159], v[2:5]
	s_cbranch_scc1 .LBB0_1236
	s_mul_i32 s6, s15, s62
	s_add_i32 s6, s6, s86
	s_mul_hi_i32 s7, s6, 0x2aaaaaab
	s_lshr_b32 s21, s7, 31
	s_ashr_i32 s7, s7, 3
	s_add_i32 s21, s7, s21
	s_mul_i32 s7, s21, 48
	v_mov_b32_e32 v97, v196
	s_sub_i32 s6, s6, s7
	s_ashr_i32 s7, s6, 31
	v_and_b32_e32 v98, 15, v97
	v_and_b32_e32 v99, 64, v97
	v_ashrrev_i32_e32 v100, 1, v97
	v_lshrrev_b32_e32 v97, 2, v97
	v_and_or_b32 v98, v100, s52, v98
	s_lshl_b32 s21, s21, 7
	v_and_b32_e32 v97, 12, v97
	s_lshl_b64 s[6:7], s[6:7], 20
	v_or3_b32 v100, v99, v97, s21
	v_ashrrev_i32_e32 v99, 31, v98
	s_add_u32 s6, s96, s6
	v_lshlrev_b64 v[102:103], 12, v[98:99]
	s_addc_u32 s7, s97, s7
	v_ashrrev_i32_e32 v101, 31, v100
	v_cvt_pk_bf16_f32 v62, v62, v63
	v_cvt_pk_bf16_f32 v63, v64, v65
	v_lshl_add_u64 v[64:65], s[6:7], 0, v[102:103]
	v_lshlrev_b64 v[100:101], 1, v[100:101]
	v_lshl_add_u64 v[64:65], v[64:65], 0, v[100:101]
	v_cvt_pk_bf16_f32 v50, v50, v51
	v_cvt_pk_bf16_f32 v51, v52, v53
	global_store_dwordx2 v[64:65], v[50:51], off offset:96
	v_or_b32_e32 v50, 16, v98
	v_ashrrev_i32_e32 v51, 31, v50
	v_lshlrev_b64 v[50:51], 12, v[50:51]
	v_cvt_pk_bf16_f32 v46, v46, v47
	v_cvt_pk_bf16_f32 v47, v48, v49
	v_lshl_add_u64 v[48:49], s[6:7], 0, v[50:51]
	v_lshl_add_u64 v[48:49], v[48:49], 0, v[100:101]
	v_cvt_pk_bf16_f32 v34, v34, v35
	v_cvt_pk_bf16_f32 v35, v36, v37
	global_store_dwordx2 v[48:49], v[34:35], off offset:96
	v_or_b32_e32 v34, 32, v98
	v_ashrrev_i32_e32 v35, 31, v34
	v_lshlrev_b64 v[34:35], 12, v[34:35]
	v_cvt_pk_bf16_f32 v30, v30, v31
	v_cvt_pk_bf16_f32 v31, v32, v33
	v_lshl_add_u64 v[32:33], s[6:7], 0, v[34:35]
	v_lshl_add_u64 v[32:33], v[32:33], 0, v[100:101]
	v_cvt_pk_bf16_f32 v18, v18, v19
	v_cvt_pk_bf16_f32 v19, v20, v21
	global_store_dwordx2 v[32:33], v[18:19], off offset:96
	v_or_b32_e32 v18, 48, v98
	v_ashrrev_i32_e32 v19, 31, v18
	v_lshlrev_b64 v[18:19], 12, v[18:19]
	v_cvt_pk_bf16_f32 v14, v14, v15
	v_cvt_pk_bf16_f32 v15, v16, v17
	v_lshl_add_u64 v[16:17], s[6:7], 0, v[18:19]
	v_lshl_add_u64 v[16:17], v[16:17], 0, v[100:101]
	v_cvt_pk_bf16_f32 v2, v2, v3
	v_cvt_pk_bf16_f32 v3, v4, v5
	v_cvt_pk_bf16_f32 v58, v58, v59
	v_cvt_pk_bf16_f32 v59, v60, v61
	v_cvt_pk_bf16_f32 v54, v54, v55
	v_cvt_pk_bf16_f32 v55, v56, v57
	v_cvt_pk_bf16_f32 v42, v42, v43
	v_cvt_pk_bf16_f32 v43, v44, v45
	v_cvt_pk_bf16_f32 v38, v38, v39
	v_cvt_pk_bf16_f32 v39, v40, v41
	v_cvt_pk_bf16_f32 v26, v26, v27
	v_cvt_pk_bf16_f32 v27, v28, v29
	v_cvt_pk_bf16_f32 v22, v22, v23
	v_cvt_pk_bf16_f32 v23, v24, v25
	v_cvt_pk_bf16_f32 v10, v10, v11
	v_cvt_pk_bf16_f32 v11, v12, v13
	v_cvt_pk_bf16_f32 v6, v6, v7
	v_cvt_pk_bf16_f32 v7, v8, v9
	global_store_dwordx2 v[16:17], v[2:3], off offset:96
	v_mov_b32_e32 v2, 0
	global_store_dwordx2 v[64:65], v[62:63], off
	global_store_dwordx2 v[64:65], v[58:59], off offset:32
	global_store_dwordx2 v[64:65], v[54:55], off offset:64
	global_store_dwordx2 v[48:49], v[46:47], off
	global_store_dwordx2 v[48:49], v[42:43], off offset:32
	global_store_dwordx2 v[48:49], v[38:39], off offset:64
	global_store_dwordx2 v[32:33], v[30:31], off
	global_store_dwordx2 v[32:33], v[26:27], off offset:32
	global_store_dwordx2 v[32:33], v[22:23], off offset:64
	global_store_dwordx2 v[16:17], v[14:15], off
	global_store_dwordx2 v[16:17], v[10:11], off offset:32
	global_store_dwordx2 v[16:17], v[6:7], off offset:64
	s_add_i32 s15, s15, 1
	s_mov_b32 s21, 0
	v_mov_b32_e32 v3, v2
	v_mov_b32_e32 v4, v2
	v_mov_b32_e32 v5, v2
	v_mov_b32_e32 v6, v2
	v_mov_b32_e32 v7, v2
	v_mov_b32_e32 v8, v2
	v_mov_b32_e32 v9, v2
	v_mov_b32_e32 v10, v2
	v_mov_b32_e32 v11, v2
	v_mov_b32_e32 v12, v2
	v_mov_b32_e32 v13, v2
	v_mov_b32_e32 v14, v2
	v_mov_b32_e32 v15, v2
	v_mov_b32_e32 v16, v2
	v_mov_b32_e32 v17, v2
	v_mov_b32_e32 v18, v2
	v_mov_b32_e32 v19, v2
	v_mov_b32_e32 v20, v2
	v_mov_b32_e32 v21, v2
	v_mov_b32_e32 v22, v2
	v_mov_b32_e32 v23, v2
	v_mov_b32_e32 v24, v2
	v_mov_b32_e32 v25, v2
	v_mov_b32_e32 v26, v2
	v_mov_b32_e32 v27, v2
	v_mov_b32_e32 v28, v2
	v_mov_b32_e32 v29, v2
	v_mov_b32_e32 v30, v2
	v_mov_b32_e32 v31, v2
	v_mov_b32_e32 v32, v2
	v_mov_b32_e32 v33, v2
	v_mov_b32_e32 v34, v2
	v_mov_b32_e32 v35, v2
	v_mov_b32_e32 v36, v2
	v_mov_b32_e32 v37, v2
	v_mov_b32_e32 v38, v2
	v_mov_b32_e32 v39, v2
	v_mov_b32_e32 v40, v2
	v_mov_b32_e32 v41, v2
	v_mov_b32_e32 v42, v2
	v_mov_b32_e32 v43, v2
	v_mov_b32_e32 v44, v2
	v_mov_b32_e32 v45, v2
	v_mov_b32_e32 v46, v2
	v_mov_b32_e32 v47, v2
	v_mov_b32_e32 v48, v2
	v_mov_b32_e32 v49, v2
	v_mov_b32_e32 v50, v2
	v_mov_b32_e32 v51, v2
	v_mov_b32_e32 v52, v2
	v_mov_b32_e32 v53, v2
	v_mov_b32_e32 v54, v2
	v_mov_b32_e32 v55, v2
	v_mov_b32_e32 v56, v2
	v_mov_b32_e32 v57, v2
	v_mov_b32_e32 v58, v2
	v_mov_b32_e32 v59, v2
	v_mov_b32_e32 v60, v2
	v_mov_b32_e32 v61, v2
	v_mov_b32_e32 v62, v2
	v_mov_b32_e32 v63, v2
	v_mov_b32_e32 v64, v2
	v_mov_b32_e32 v65, v2
